# S5 pass B rewritten too: carry Horner, B*u on f32 matrix cores, blocked scan with permlane32 carry exchange, per-wave LDS Hs/Us, gelu epilogue (same numerics)
# speedup vs baseline: 1.0397x; 1.0299x over previous
.LBB0_283:
	s_or_b64 exec, exec, s[6:7]
	s_add_u32 s10, s74, 0x12cd5c00
	s_addc_u32 s11, s75, 0
	s_add_u32 s24, s74, 0x12ce5c00
	s_addc_u32 s25, s75, 0
	s_add_u32 s26, s74, 0x12d25c00
	s_addc_u32 s27, s75, 0
	s_add_u32 s28, s74, 0x12da5c00
	s_addc_u32 s29, s75, 0
	v_mov_b32_e32 v116, v174
	s_cmpk_gt_i32 s2, 0x7ff
	s_barrier
	s_cbranch_scc1 .LBB0_300
	v_and_b32_e32 v196, 63, v174
	v_lshrrev_b32_e32 v197, 6, v174
	v_and_b32_e32 v198, 31, v196
	v_lshrrev_b32_e32 v199, 5, v196
	s_and_b32 s80, s2, 7
	v_lshl_add_u32 v200, s80, 3, v197
	v_lshl_add_u32 v201, v200, 6, v198
	v_lshlrev_b32_e32 v202, 6, v201
	v_lshl_add_u32 v202, v199, 5, v202
	global_load_dwordx4 v[24:27], v202, s[24:25] offset:0
	global_load_dwordx4 v[28:31], v202, s[24:25] offset:16
	global_load_dwordx4 v[40:43], v202, s[24:25] offset:2048
	global_load_dwordx4 v[44:47], v202, s[24:25] offset:2064
	global_load_dwordx4 v[32:35], v202, s[26:27] offset:0
	global_load_dwordx4 v[36:39], v202, s[26:27] offset:16
	global_load_dwordx4 v[48:51], v202, s[26:27] offset:2048
	global_load_dwordx4 v[52:55], v202, s[26:27] offset:2064
	v_lshlrev_b32_e32 v203, 3, v201
	s_lshl_b32 s81, s80, 7
	v_lshl_add_u32 v204, v197, 4, s81
	v_lshl_add_u32 v204, v199, 3, v204
	v_lshlrev_b32_e32 v204, 2, v204
	global_load_dwordx4 v[140:143], v204, s[42:43]
	global_load_dwordx4 v[144:147], v204, s[42:43] offset:16
	v_lshl_add_u32 v205, v198, 12, v204
	v_lshlrev_b32_e32 v206, 2, v198
	v_lshl_add_u32 v207, v200, 6, v196
	v_lshlrev_b32_e32 v207, 3, v207
	v_mov_b32_e32 v254, 0x358637bd
	s_mov_b32 s8, 0
	s_mov_b32 s9, -1
	global_load_dwordx2 v[0:1], v203, s[10:11]
	global_load_dwordx2 v[2:3], v203, s[10:11] offset:256
	s_waitcnt vmcnt(0)
	v_mul_f32_e32 v58, v1, v1
	v_mul_f32_e32 v59, v1, v0
	v_fma_f32 v4, v0, v0, -v58
	v_fma_f32 v5, v0, v1, v59
	v_mul_f32_e32 v128, v3, v3
	v_mul_f32_e32 v129, v3, v2
	v_fma_f32 v6, v2, v2, -v128
	v_fma_f32 v7, v2, v3, v129
	v_mul_f32_e32 v58, v5, v5
	v_mul_f32_e32 v59, v5, v4
	v_fma_f32 v8, v4, v4, -v58
	v_fma_f32 v9, v4, v5, v59
	v_mul_f32_e32 v128, v7, v7
	v_mul_f32_e32 v129, v7, v6
	v_fma_f32 v10, v6, v6, -v128
	v_fma_f32 v11, v6, v7, v129
	v_mul_f32_e32 v58, v9, v9
	v_mul_f32_e32 v59, v9, v8
	v_fma_f32 v14, v8, v8, -v58
	v_fma_f32 v15, v8, v9, v59
	v_mul_f32_e32 v128, v11, v11
	v_mul_f32_e32 v129, v11, v10
	v_fma_f32 v16, v10, v10, -v128
	v_fma_f32 v17, v10, v11, v129
	s_mov_b32 s82, s2
	s_lshr_b32 s4, s82, 10
	s_bfe_u32 s6, s82, 0x70003
	s_lshl_b32 s4, s4, 13
	s_lshl_b32 s6, s6, 6
	s_add_i32 s31, s4, s6
	s_lshl_b32 s6, s31, 12
	s_add_u32 s84, s38, s6
	s_addc_u32 s85, s39, 0
	s_add_u32 s88, s84, 0x20000
	s_addc_u32 s89, s85, 0
	s_lshl_b32 s6, s31, 2
	s_add_u32 s86, s22, s6
	s_addc_u32 s87, s23, 0
	global_load_dwordx4 v[178:181], v205, s[84:85]
	global_load_dwordx4 v[182:185], v205, s[84:85] offset:16
	global_load_dword v194, v206, s[86:87]
	global_load_dwordx4 v[186:189], v205, s[88:89]
	global_load_dwordx4 v[190:193], v205, s[88:89] offset:16
	global_load_dword v195, v206, s[86:87] offset:128
.Ls5a_item:
	s_add_i32 s83, s82, 0x100
	s_cmpk_gt_i32 s83, 0x7ff
	s_cselect_b32 s83, s82, s83
	s_lshr_b32 s4, s83, 10
	s_bfe_u32 s6, s83, 0x70003
	s_lshl_b32 s4, s4, 13
	s_lshl_b32 s6, s6, 6
	s_add_i32 s32, s4, s6
	s_lshl_b32 s6, s32, 12
	s_add_u32 s90, s38, s6
	s_addc_u32 s91, s39, 0
	s_add_u32 s94, s90, 0x20000
	s_addc_u32 s95, s91, 0
	s_lshl_b32 s6, s32, 2
	s_add_u32 s92, s22, s6
	s_addc_u32 s93, s23, 0
	v_mov_b32_e32 v18, 0
	v_mov_b32_e32 v19, 0
	v_mov_b32_e32 v22, 0
	v_mov_b32_e32 v23, 0
	s_waitcnt vmcnt(3)
	v_fmamk_f32 v56, v194, 0x3a800000, v254
	v_rsq_f32_e32 v56, v56
	s_nop 0
	v_pk_mul_f32 v[148:149], v[178:179], v[56:57] op_sel_hi:[1,0]
	v_pk_mul_f32 v[150:151], v[180:181], v[56:57] op_sel_hi:[1,0]
	v_pk_mul_f32 v[152:153], v[182:183], v[56:57] op_sel_hi:[1,0]
	v_pk_mul_f32 v[154:155], v[184:185], v[56:57] op_sel_hi:[1,0]
	v_pk_mul_f32 v[148:149], v[140:141], v[148:149]
	v_pk_mul_f32 v[150:151], v[142:143], v[150:151]
	v_pk_mul_f32 v[152:153], v[144:145], v[152:153]
	v_pk_mul_f32 v[154:155], v[146:147], v[154:155]
	global_load_dwordx4 v[178:181], v205, s[90:91]
	global_load_dwordx4 v[182:185], v205, s[90:91] offset:16
	global_load_dword v194, v206, s[92:93]
	s_nop 1
	v_mfma_f32_32x32x2_f32 v[64:79], v148, v24, 0
	v_mfma_f32_32x32x2_f32 v[80:95], v148, v32, 0
	v_mfma_f32_32x32x2_f32 v[96:111], v148, v40, 0
	v_mfma_f32_32x32x2_f32 v[112:127], v148, v48, 0
	v_mfma_f32_32x32x2_f32 v[64:79], v149, v25, v[64:79]
	v_mfma_f32_32x32x2_f32 v[80:95], v149, v33, v[80:95]
	v_mfma_f32_32x32x2_f32 v[96:111], v149, v41, v[96:111]
	v_mfma_f32_32x32x2_f32 v[112:127], v149, v49, v[112:127]
	v_mfma_f32_32x32x2_f32 v[64:79], v150, v26, v[64:79]
	v_mfma_f32_32x32x2_f32 v[80:95], v150, v34, v[80:95]
	v_mfma_f32_32x32x2_f32 v[96:111], v150, v42, v[96:111]
	v_mfma_f32_32x32x2_f32 v[112:127], v150, v50, v[112:127]
	v_mfma_f32_32x32x2_f32 v[64:79], v151, v27, v[64:79]
	v_mfma_f32_32x32x2_f32 v[80:95], v151, v35, v[80:95]
	v_mfma_f32_32x32x2_f32 v[96:111], v151, v43, v[96:111]
	v_mfma_f32_32x32x2_f32 v[112:127], v151, v51, v[112:127]
	v_mfma_f32_32x32x2_f32 v[64:79], v152, v28, v[64:79]
	v_mfma_f32_32x32x2_f32 v[80:95], v152, v36, v[80:95]
	v_mfma_f32_32x32x2_f32 v[96:111], v152, v44, v[96:111]
	v_mfma_f32_32x32x2_f32 v[112:127], v152, v52, v[112:127]
	v_mfma_f32_32x32x2_f32 v[64:79], v153, v29, v[64:79]
	v_mfma_f32_32x32x2_f32 v[80:95], v153, v37, v[80:95]
	v_mfma_f32_32x32x2_f32 v[96:111], v153, v45, v[96:111]
	v_mfma_f32_32x32x2_f32 v[112:127], v153, v53, v[112:127]
	v_mfma_f32_32x32x2_f32 v[64:79], v154, v30, v[64:79]
	v_mfma_f32_32x32x2_f32 v[80:95], v154, v38, v[80:95]
	v_mfma_f32_32x32x2_f32 v[96:111], v154, v46, v[96:111]
	v_mfma_f32_32x32x2_f32 v[112:127], v154, v54, v[112:127]
	v_mfma_f32_32x32x2_f32 v[64:79], v155, v31, v[64:79]
	v_mfma_f32_32x32x2_f32 v[80:95], v155, v39, v[80:95]
	v_mfma_f32_32x32x2_f32 v[96:111], v155, v47, v[96:111]
	v_mfma_f32_32x32x2_f32 v[112:127], v155, v55, v[112:127]
	s_nop 7
	s_nop 7
	s_nop 1
	v_fma_f32 v58, v64, v0, v65
	v_fma_f32 v59, v64, v1, v81
	v_fma_f32 v65, -v80, v1, v58
	v_fma_f32 v81, v80, v0, v59
	v_fma_f32 v128, v96, v2, v97
	v_fma_f32 v129, v96, v3, v113
	v_fma_f32 v97, -v112, v3, v128
	v_fma_f32 v113, v112, v2, v129
	v_fma_f32 v58, v68, v0, v69
	v_fma_f32 v59, v68, v1, v85
	v_fma_f32 v69, -v84, v1, v58
	v_fma_f32 v85, v84, v0, v59
	v_fma_f32 v128, v100, v2, v101
	v_fma_f32 v129, v100, v3, v117
	v_fma_f32 v101, -v116, v3, v128
	v_fma_f32 v117, v116, v2, v129
	v_fma_f32 v58, v72, v0, v73
	v_fma_f32 v59, v72, v1, v89
	v_fma_f32 v73, -v88, v1, v58
	v_fma_f32 v89, v88, v0, v59
	v_fma_f32 v128, v104, v2, v105
	v_fma_f32 v129, v104, v3, v121
	v_fma_f32 v105, -v120, v3, v128
	v_fma_f32 v121, v120, v2, v129
	v_fma_f32 v58, v76, v0, v77
	v_fma_f32 v59, v76, v1, v93
	v_fma_f32 v77, -v92, v1, v58
	v_fma_f32 v93, v92, v0, v59
	v_fma_f32 v128, v108, v2, v109
	v_fma_f32 v129, v108, v3, v125
	v_fma_f32 v109, -v124, v3, v128
	v_fma_f32 v125, v124, v2, v129
	v_fma_f32 v58, v65, v0, v66
	v_fma_f32 v59, v65, v1, v82
	v_fma_f32 v66, -v81, v1, v58
	v_fma_f32 v82, v81, v0, v59
	v_fma_f32 v128, v97, v2, v98
	v_fma_f32 v129, v97, v3, v114
	v_fma_f32 v98, -v113, v3, v128
	v_fma_f32 v114, v113, v2, v129
	v_fma_f32 v58, v69, v0, v70
	v_fma_f32 v59, v69, v1, v86
	v_fma_f32 v70, -v85, v1, v58
	v_fma_f32 v86, v85, v0, v59
	v_fma_f32 v128, v101, v2, v102
	v_fma_f32 v129, v101, v3, v118
	v_fma_f32 v102, -v117, v3, v128
	v_fma_f32 v118, v117, v2, v129
	v_fma_f32 v58, v73, v0, v74
	v_fma_f32 v59, v73, v1, v90
	v_fma_f32 v74, -v89, v1, v58
	v_fma_f32 v90, v89, v0, v59
	v_fma_f32 v128, v105, v2, v106
	v_fma_f32 v129, v105, v3, v122
	v_fma_f32 v106, -v121, v3, v128
	v_fma_f32 v122, v121, v2, v129
	v_fma_f32 v58, v77, v0, v78
	v_fma_f32 v59, v77, v1, v94
	v_fma_f32 v78, -v93, v1, v58
	v_fma_f32 v94, v93, v0, v59
	v_fma_f32 v128, v109, v2, v110
	v_fma_f32 v129, v109, v3, v126
	v_fma_f32 v110, -v125, v3, v128
	v_fma_f32 v126, v125, v2, v129
	v_fma_f32 v58, v66, v0, v67
	v_fma_f32 v59, v66, v1, v83
	v_fma_f32 v67, -v82, v1, v58
	v_fma_f32 v83, v82, v0, v59
	v_fma_f32 v128, v98, v2, v99
	v_fma_f32 v129, v98, v3, v115
	v_fma_f32 v99, -v114, v3, v128
	v_fma_f32 v115, v114, v2, v129
	v_fma_f32 v58, v70, v0, v71
	v_fma_f32 v59, v70, v1, v87
	v_fma_f32 v71, -v86, v1, v58
	v_fma_f32 v87, v86, v0, v59
	v_fma_f32 v128, v102, v2, v103
	v_fma_f32 v129, v102, v3, v119
	v_fma_f32 v103, -v118, v3, v128
	v_fma_f32 v119, v118, v2, v129
	v_fma_f32 v58, v74, v0, v75
	v_fma_f32 v59, v74, v1, v91
	v_fma_f32 v75, -v90, v1, v58
	v_fma_f32 v91, v90, v0, v59
	v_fma_f32 v128, v106, v2, v107
	v_fma_f32 v129, v106, v3, v123
	v_fma_f32 v107, -v122, v3, v128
	v_fma_f32 v123, v122, v2, v129
	v_fma_f32 v58, v78, v0, v79
	v_fma_f32 v59, v78, v1, v95
	v_fma_f32 v79, -v94, v1, v58
	v_fma_f32 v95, v94, v0, v59
	v_fma_f32 v128, v110, v2, v111
	v_fma_f32 v129, v110, v3, v127
	v_fma_f32 v111, -v126, v3, v128
	v_fma_f32 v127, v126, v2, v129
	v_fma_f32 v58, v18, v14, v67
	v_fma_f32 v59, v18, v15, v83
	v_fma_f32 v18, -v19, v15, v58
	v_fma_f32 v19, v19, v14, v59
	v_fma_f32 v128, v22, v16, v99
	v_fma_f32 v129, v22, v17, v115
	v_fma_f32 v22, -v23, v17, v128
	v_fma_f32 v23, v23, v16, v129
	v_fma_f32 v58, v18, v14, v71
	v_fma_f32 v59, v18, v15, v87
	v_fma_f32 v18, -v19, v15, v58
	v_fma_f32 v19, v19, v14, v59
	v_fma_f32 v128, v22, v16, v103
	v_fma_f32 v129, v22, v17, v119
	v_fma_f32 v22, -v23, v17, v128
	v_fma_f32 v23, v23, v16, v129
	v_fma_f32 v58, v18, v14, v75
	v_fma_f32 v59, v18, v15, v91
	v_fma_f32 v18, -v19, v15, v58
	v_fma_f32 v19, v19, v14, v59
	v_fma_f32 v128, v22, v16, v107
	v_fma_f32 v129, v22, v17, v123
	v_fma_f32 v22, -v23, v17, v128
	v_fma_f32 v23, v23, v16, v129
	v_fma_f32 v58, v18, v14, v79
	v_fma_f32 v59, v18, v15, v95
	v_fma_f32 v18, -v19, v15, v58
	v_fma_f32 v19, v19, v14, v59
	v_fma_f32 v128, v22, v16, v111
	v_fma_f32 v129, v22, v17, v127
	v_fma_f32 v22, -v23, v17, v128
	v_fma_f32 v23, v23, v16, v129
	s_waitcnt vmcnt(3)
	v_fmamk_f32 v56, v195, 0x3a800000, v254
	v_rsq_f32_e32 v56, v56
	s_nop 0
	v_pk_mul_f32 v[148:149], v[186:187], v[56:57] op_sel_hi:[1,0]
	v_pk_mul_f32 v[150:151], v[188:189], v[56:57] op_sel_hi:[1,0]
	v_pk_mul_f32 v[152:153], v[190:191], v[56:57] op_sel_hi:[1,0]
	v_pk_mul_f32 v[154:155], v[192:193], v[56:57] op_sel_hi:[1,0]
	v_pk_mul_f32 v[148:149], v[140:141], v[148:149]
	v_pk_mul_f32 v[150:151], v[142:143], v[150:151]
	v_pk_mul_f32 v[152:153], v[144:145], v[152:153]
	v_pk_mul_f32 v[154:155], v[146:147], v[154:155]
	global_load_dwordx4 v[186:189], v205, s[94:95]
	global_load_dwordx4 v[190:193], v205, s[94:95] offset:16
	global_load_dword v195, v206, s[92:93] offset:128
	s_nop 1
	v_mfma_f32_32x32x2_f32 v[64:79], v148, v24, 0
	v_mfma_f32_32x32x2_f32 v[80:95], v148, v32, 0
	v_mfma_f32_32x32x2_f32 v[96:111], v148, v40, 0
	v_mfma_f32_32x32x2_f32 v[112:127], v148, v48, 0
	v_mfma_f32_32x32x2_f32 v[64:79], v149, v25, v[64:79]
	v_mfma_f32_32x32x2_f32 v[80:95], v149, v33, v[80:95]
	v_mfma_f32_32x32x2_f32 v[96:111], v149, v41, v[96:111]
	v_mfma_f32_32x32x2_f32 v[112:127], v149, v49, v[112:127]
	v_mfma_f32_32x32x2_f32 v[64:79], v150, v26, v[64:79]
	v_mfma_f32_32x32x2_f32 v[80:95], v150, v34, v[80:95]
	v_mfma_f32_32x32x2_f32 v[96:111], v150, v42, v[96:111]
	v_mfma_f32_32x32x2_f32 v[112:127], v150, v50, v[112:127]
	v_mfma_f32_32x32x2_f32 v[64:79], v151, v27, v[64:79]
	v_mfma_f32_32x32x2_f32 v[80:95], v151, v35, v[80:95]
	v_mfma_f32_32x32x2_f32 v[96:111], v151, v43, v[96:111]
	v_mfma_f32_32x32x2_f32 v[112:127], v151, v51, v[112:127]
	v_mfma_f32_32x32x2_f32 v[64:79], v152, v28, v[64:79]
	v_mfma_f32_32x32x2_f32 v[80:95], v152, v36, v[80:95]
	v_mfma_f32_32x32x2_f32 v[96:111], v152, v44, v[96:111]
	v_mfma_f32_32x32x2_f32 v[112:127], v152, v52, v[112:127]
	v_mfma_f32_32x32x2_f32 v[64:79], v153, v29, v[64:79]
	v_mfma_f32_32x32x2_f32 v[80:95], v153, v37, v[80:95]
	v_mfma_f32_32x32x2_f32 v[96:111], v153, v45, v[96:111]
	v_mfma_f32_32x32x2_f32 v[112:127], v153, v53, v[112:127]
	v_mfma_f32_32x32x2_f32 v[64:79], v154, v30, v[64:79]
	v_mfma_f32_32x32x2_f32 v[80:95], v154, v38, v[80:95]
	v_mfma_f32_32x32x2_f32 v[96:111], v154, v46, v[96:111]
	v_mfma_f32_32x32x2_f32 v[112:127], v154, v54, v[112:127]
	v_mfma_f32_32x32x2_f32 v[64:79], v155, v31, v[64:79]
	v_mfma_f32_32x32x2_f32 v[80:95], v155, v39, v[80:95]
	v_mfma_f32_32x32x2_f32 v[96:111], v155, v47, v[96:111]
	v_mfma_f32_32x32x2_f32 v[112:127], v155, v55, v[112:127]
	s_nop 7
	s_nop 7
	s_nop 1
	v_fma_f32 v58, v64, v0, v65
	v_fma_f32 v59, v64, v1, v81
	v_fma_f32 v65, -v80, v1, v58
	v_fma_f32 v81, v80, v0, v59
	v_fma_f32 v128, v96, v2, v97
	v_fma_f32 v129, v96, v3, v113
	v_fma_f32 v97, -v112, v3, v128
	v_fma_f32 v113, v112, v2, v129
	v_fma_f32 v58, v68, v0, v69
	v_fma_f32 v59, v68, v1, v85
	v_fma_f32 v69, -v84, v1, v58
	v_fma_f32 v85, v84, v0, v59
	v_fma_f32 v128, v100, v2, v101
	v_fma_f32 v129, v100, v3, v117
	v_fma_f32 v101, -v116, v3, v128
	v_fma_f32 v117, v116, v2, v129
	v_fma_f32 v58, v72, v0, v73
	v_fma_f32 v59, v72, v1, v89
	v_fma_f32 v73, -v88, v1, v58
	v_fma_f32 v89, v88, v0, v59
	v_fma_f32 v128, v104, v2, v105
	v_fma_f32 v129, v104, v3, v121
	v_fma_f32 v105, -v120, v3, v128
	v_fma_f32 v121, v120, v2, v129
	v_fma_f32 v58, v76, v0, v77
	v_fma_f32 v59, v76, v1, v93
	v_fma_f32 v77, -v92, v1, v58
	v_fma_f32 v93, v92, v0, v59
	v_fma_f32 v128, v108, v2, v109
	v_fma_f32 v129, v108, v3, v125
	v_fma_f32 v109, -v124, v3, v128
	v_fma_f32 v125, v124, v2, v129
	v_fma_f32 v58, v65, v0, v66
	v_fma_f32 v59, v65, v1, v82
	v_fma_f32 v66, -v81, v1, v58
	v_fma_f32 v82, v81, v0, v59
	v_fma_f32 v128, v97, v2, v98
	v_fma_f32 v129, v97, v3, v114
	v_fma_f32 v98, -v113, v3, v128
	v_fma_f32 v114, v113, v2, v129
	v_fma_f32 v58, v69, v0, v70
	v_fma_f32 v59, v69, v1, v86
	v_fma_f32 v70, -v85, v1, v58
	v_fma_f32 v86, v85, v0, v59
	v_fma_f32 v128, v101, v2, v102
	v_fma_f32 v129, v101, v3, v118
	v_fma_f32 v102, -v117, v3, v128
	v_fma_f32 v118, v117, v2, v129
	v_fma_f32 v58, v73, v0, v74
	v_fma_f32 v59, v73, v1, v90
	v_fma_f32 v74, -v89, v1, v58
	v_fma_f32 v90, v89, v0, v59
	v_fma_f32 v128, v105, v2, v106
	v_fma_f32 v129, v105, v3, v122
	v_fma_f32 v106, -v121, v3, v128
	v_fma_f32 v122, v121, v2, v129
	v_fma_f32 v58, v77, v0, v78
	v_fma_f32 v59, v77, v1, v94
	v_fma_f32 v78, -v93, v1, v58
	v_fma_f32 v94, v93, v0, v59
	v_fma_f32 v128, v109, v2, v110
	v_fma_f32 v129, v109, v3, v126
	v_fma_f32 v110, -v125, v3, v128
	v_fma_f32 v126, v125, v2, v129
	v_fma_f32 v58, v66, v0, v67
	v_fma_f32 v59, v66, v1, v83
	v_fma_f32 v67, -v82, v1, v58
	v_fma_f32 v83, v82, v0, v59
	v_fma_f32 v128, v98, v2, v99
	v_fma_f32 v129, v98, v3, v115
	v_fma_f32 v99, -v114, v3, v128
	v_fma_f32 v115, v114, v2, v129
	v_fma_f32 v58, v70, v0, v71
	v_fma_f32 v59, v70, v1, v87
	v_fma_f32 v71, -v86, v1, v58
	v_fma_f32 v87, v86, v0, v59
	v_fma_f32 v128, v102, v2, v103
	v_fma_f32 v129, v102, v3, v119
	v_fma_f32 v103, -v118, v3, v128
	v_fma_f32 v119, v118, v2, v129
	v_fma_f32 v58, v74, v0, v75
	v_fma_f32 v59, v74, v1, v91
	v_fma_f32 v75, -v90, v1, v58
	v_fma_f32 v91, v90, v0, v59
	v_fma_f32 v128, v106, v2, v107
	v_fma_f32 v129, v106, v3, v123
	v_fma_f32 v107, -v122, v3, v128
	v_fma_f32 v123, v122, v2, v129
	v_fma_f32 v58, v78, v0, v79
	v_fma_f32 v59, v78, v1, v95
	v_fma_f32 v79, -v94, v1, v58
	v_fma_f32 v95, v94, v0, v59
	v_fma_f32 v128, v110, v2, v111
	v_fma_f32 v129, v110, v3, v127
	v_fma_f32 v111, -v126, v3, v128
	v_fma_f32 v127, v126, v2, v129
	v_fma_f32 v58, v18, v14, v67
	v_fma_f32 v59, v18, v15, v83
	v_fma_f32 v18, -v19, v15, v58
	v_fma_f32 v19, v19, v14, v59
	v_fma_f32 v128, v22, v16, v99
	v_fma_f32 v129, v22, v17, v115
	v_fma_f32 v22, -v23, v17, v128
	v_fma_f32 v23, v23, v16, v129
	v_fma_f32 v58, v18, v14, v71
	v_fma_f32 v59, v18, v15, v87
	v_fma_f32 v18, -v19, v15, v58
	v_fma_f32 v19, v19, v14, v59
	v_fma_f32 v128, v22, v16, v103
	v_fma_f32 v129, v22, v17, v119
	v_fma_f32 v22, -v23, v17, v128
	v_fma_f32 v23, v23, v16, v129
	v_fma_f32 v58, v18, v14, v75
	v_fma_f32 v59, v18, v15, v91
	v_fma_f32 v18, -v19, v15, v58
	v_fma_f32 v19, v19, v14, v59
	v_fma_f32 v128, v22, v16, v107
	v_fma_f32 v129, v22, v17, v123
	v_fma_f32 v22, -v23, v17, v128
	v_fma_f32 v23, v23, v16, v129
	v_fma_f32 v58, v18, v14, v79
	v_fma_f32 v59, v18, v15, v95
	v_fma_f32 v18, -v19, v15, v58
	v_fma_f32 v19, v19, v14, v59
	v_fma_f32 v128, v22, v16, v111
	v_fma_f32 v129, v22, v17, v127
	v_fma_f32 v22, -v23, v17, v128
	v_fma_f32 v23, v23, v16, v129
	v_mov_b32_e32 v130, v18
	v_mov_b32_e32 v131, v19
	v_mov_b32_e32 v132, v22
	v_mov_b32_e32 v133, v23
	s_nop 1
	v_permlane32_swap_b32_e32 v18, v130
	v_permlane32_swap_b32_e32 v19, v131
	v_permlane32_swap_b32_e32 v22, v132
	v_permlane32_swap_b32_e32 v23, v133
	v_fma_f32 v58, v18, v8, v130
	v_fma_f32 v59, v18, v9, v131
	v_fma_f32 v134, -v19, v9, v58
	v_fma_f32 v135, v19, v8, v59
	v_fma_f32 v128, v22, v10, v132
	v_fma_f32 v129, v22, v11, v133
	v_fma_f32 v136, -v23, v11, v128
	v_fma_f32 v137, v23, v10, v129
	v_cndmask_b32_e64 v134, v134, v136, s[8:9]
	v_cndmask_b32_e64 v135, v135, v137, s[8:9]
	s_lshr_b32 s4, s82, 3
	s_lshl_b32 s4, s4, 15
	s_add_u32 s6, s28, s4
	s_addc_u32 s7, s29, 0
	global_store_dwordx2 v207, v[134:135], s[6:7]
	s_add_i32 s82, s82, 0x100
	s_cmpk_lt_i32 s82, 0x800
	s_cbranch_scc1 .Ls5a_item

.LBB0_320:
	s_or_b64 exec, exec, s[6:7]
	s_add_u32 s12, s74, 0x10ae0000
	s_addc_u32 s13, s75, 0
	v_mov_b32_e32 v69, v174
	s_cmpk_gt_i32 s2, 0x8ff
	s_barrier
	s_cbranch_scc1 .LBB0_364
	v_and_b32_e32 v196, 63, v174
	v_lshrrev_b32_e32 v197, 6, v174
	v_and_b32_e32 v198, 31, v196
	v_lshrrev_b32_e32 v199, 5, v196
	s_and_b32 s80, s2, 7
	v_lshl_add_u32 v200, s80, 3, v197
	v_lshl_add_u32 v201, v200, 6, v198
	v_lshlrev_b32_e32 v202, 6, v201
	v_lshl_add_u32 v202, v199, 5, v202
	global_load_dwordx4 v[24:27], v202, s[24:25] offset:0
	global_load_dwordx4 v[28:31], v202, s[24:25] offset:16
	global_load_dwordx4 v[40:43], v202, s[24:25] offset:2048
	global_load_dwordx4 v[44:47], v202, s[24:25] offset:2064
	global_load_dwordx4 v[32:35], v202, s[26:27] offset:0
	global_load_dwordx4 v[36:39], v202, s[26:27] offset:16
	global_load_dwordx4 v[48:51], v202, s[26:27] offset:2048
	global_load_dwordx4 v[52:55], v202, s[26:27] offset:2064
	v_lshlrev_b32_e32 v203, 3, v201
	s_lshl_b32 s81, s80, 7
	v_lshl_add_u32 v204, v197, 4, s81
	v_lshl_add_u32 v204, v199, 3, v204
	v_lshlrev_b32_e32 v204, 2, v204
	global_load_dwordx4 v[140:143], v204, s[42:43]
	global_load_dwordx4 v[144:147], v204, s[42:43] offset:16
	v_lshl_add_u32 v205, v198, 12, v204
	v_lshlrev_b32_e32 v206, 2, v198
	v_lshl_add_u32 v207, v200, 6, v196
	v_lshlrev_b32_e32 v207, 3, v207
	v_mov_b32_e32 v254, 0x358637bd
	s_mov_b32 s8, 0
	s_mov_b32 s9, -1
	global_load_dwordx2 v[56:57], v203, s[10:11]
	global_load_dwordx2 v[58:59], v203, s[10:11] offset:256
	s_add_u32 s30, s74, 0x12cddc00
	s_addc_u32 s31, s75, 0
	global_load_dwordx2 v[18:19], v207, s[30:31]
	v_and_b32_e32 v172, 15, v196
	v_lshrrev_b32_e32 v173, 4, v196
	v_lshl_add_u32 v60, v200, 4, v172
	v_lshlrev_b32_e32 v202, 8, v60
	v_lshl_add_u32 v202, v173, 3, v202
	s_add_u32 s84, s74, 0x12d65c00
	s_addc_u32 s85, s75, 0
	global_load_dwordx2 v[64:65], v202, s[84:85] offset:0
	global_load_dwordx2 v[66:67], v202, s[84:85] offset:128
	global_load_dwordx2 v[68:69], v202, s[84:85] offset:32
	global_load_dwordx2 v[70:71], v202, s[84:85] offset:160
	global_load_dwordx2 v[72:73], v202, s[84:85] offset:64
	global_load_dwordx2 v[74:75], v202, s[84:85] offset:192
	global_load_dwordx2 v[76:77], v202, s[84:85] offset:96
	global_load_dwordx2 v[78:79], v202, s[84:85] offset:224
	v_lshlrev_b32_e32 v203, 2, v60
	global_load_dword v224, v203, s[58:59]
	v_mov_b32_e32 v177, 0x05040100
	v_mov_b32_e32 v244, 0x07060302
	v_min_u32_e32 v60, 7, v198
	v_lshl_add_u32 v225, v60, 12, v204
	v_lshlrev_b32_e32 v226, 2, v60
	v_mul_u32_u24_e32 v60, 0x2c00, v197
	v_mul_u32_u24_e32 v229, 0x440, v199
	v_lshl_add_u32 v229, v198, 2, v229
	v_add_u32_e32 v229, v229, v60
	v_mul_u32_u24_e32 v230, 0x110, v172
	v_lshl_add_u32 v230, v173, 4, v230
	v_add_u32_e32 v230, v230, v60
	v_lshlrev_b32_e32 v231, 6, v198
	v_lshl_add_u32 v231, v199, 5, v231
	v_add_u32_e32 v245, 0x2200, v60
	v_add_u32_e32 v231, v231, v245
	v_lshlrev_b32_e32 v232, 8, v173
	v_lshl_add_u32 v232, v172, 2, v232
	v_add_u32_e32 v232, v232, v245
	v_lshl_add_u32 v60, v200, 4, v172
	v_lshlrev_b32_e32 v60, 1, v60
	v_lshl_add_u32 v233, v173, 13, v60
	v_add_u32_e32 v241, 0x800, v233
	v_add_u32_e32 v242, 0x1000, v233
	v_add_u32_e32 v243, 0x1800, v233
	s_waitcnt vmcnt(0)
	v_mov_b32_e32 v0, v56
	v_mov_b32_e32 v4, v57
	v_mov_b32_e32 v8, v58
	v_mov_b32_e32 v14, v59
	v_mul_f32_e32 v168, v4, v4
	v_mul_f32_e32 v169, v4, v0
	v_fma_f32 v1, v0, v0, -v168
	v_fma_f32 v5, v0, v4, v169
	v_mul_f32_e32 v170, v14, v14
	v_mul_f32_e32 v171, v14, v8
	v_fma_f32 v9, v8, v8, -v170
	v_fma_f32 v15, v8, v14, v171
	v_mul_f32_e32 v168, v5, v4
	v_mul_f32_e32 v169, v5, v0
	v_fma_f32 v2, v1, v0, -v168
	v_fma_f32 v6, v1, v4, v169
	v_mul_f32_e32 v170, v15, v14
	v_mul_f32_e32 v171, v15, v8
	v_fma_f32 v10, v9, v8, -v170
	v_fma_f32 v16, v9, v14, v171
	v_mul_f32_e32 v168, v5, v5
	v_mul_f32_e32 v169, v5, v1
	v_fma_f32 v3, v1, v1, -v168
	v_fma_f32 v7, v1, v5, v169
	v_mul_f32_e32 v170, v15, v15
	v_mul_f32_e32 v171, v15, v9
	v_fma_f32 v11, v9, v9, -v170
	v_fma_f32 v17, v9, v15, v171
	v_perm_b32 v208, v66, v64, v177
	v_perm_b32 v209, v66, v64, v244
	v_perm_b32 v210, v67, v65, v177
	v_perm_b32 v211, v67, v65, v244
	v_perm_b32 v212, v70, v68, v177
	v_perm_b32 v213, v70, v68, v244
	v_perm_b32 v214, v71, v69, v177
	v_perm_b32 v215, v71, v69, v244
	v_perm_b32 v216, v74, v72, v177
	v_perm_b32 v217, v74, v72, v244
	v_perm_b32 v218, v75, v73, v177
	v_perm_b32 v219, v75, v73, v244
	v_perm_b32 v220, v78, v76, v177
	v_perm_b32 v221, v78, v76, v244
	v_perm_b32 v222, v79, v77, v177
	v_perm_b32 v223, v79, v77, v244
	v_mov_b32_e32 v22, 0
	v_mov_b32_e32 v23, 0
	s_mov_b32 s98, -1
	s_mov_b32 s99, 0
	s_mov_b32 s82, s2
	s_lshr_b32 s4, s82, 10
	s_bfe_u32 s6, s82, 0x70003
	s_lshl_b32 s4, s4, 13
	s_lshl_b32 s6, s6, 6
	s_add_i32 s31, s4, s6
	s_lshl_b32 s6, s31, 12
	s_add_u32 s84, s38, s6
	s_addc_u32 s85, s39, 0
	s_add_u32 s88, s84, 0x20000
	s_addc_u32 s89, s85, 0
	s_lshl_b32 s6, s31, 2
	s_add_u32 s86, s22, s6
	s_addc_u32 s87, s23, 0
	global_load_dwordx4 v[178:181], v205, s[84:85]
	global_load_dwordx4 v[182:185], v205, s[84:85] offset:16
	global_load_dword v194, v206, s[86:87]
	global_load_dwordx4 v[186:189], v205, s[88:89]
	global_load_dwordx4 v[190:193], v205, s[88:89] offset:16
	global_load_dword v195, v206, s[86:87] offset:128
.Ls5b_item:
	s_cmpk_gt_i32 s82, 0x7ff
	s_cbranch_scc1 .Ls5b_dec_s
	s_mov_b32 s35, 0
	s_lshr_b32 s46, s82, 10
	s_bfe_u32 s52, s82, 0x70003
	s_lshl_b32 s4, s46, 13
	s_lshl_b32 s6, s52, 6
	s_add_i32 s31, s4, s6
	s_branch .Ls5b_dec_done
.Ls5b_dec_s:
	s_mov_b32 s35, 1
	s_sub_i32 s4, s82, 0x800
	s_lshr_b32 s46, s4, 3
	s_mov_b32 s52, 0
	s_lshl_b32 s4, s46, 3
	s_add_i32 s31, s4, 0x4000
.Ls5b_dec_done:
	s_add_i32 s83, s82, 0x100
	s_cmpk_gt_i32 s83, 0x8ff
	s_cselect_b32 s83, s82, s83
	s_cmpk_gt_i32 s83, 0x7ff
	s_cbranch_scc1 .Ls5b_nx_s
	s_lshr_b32 s4, s83, 10
	s_bfe_u32 s6, s83, 0x70003
	s_lshl_b32 s4, s4, 13
	s_lshl_b32 s6, s6, 6
	s_add_i32 s32, s4, s6
	s_lshl_b32 s6, s32, 12
	s_add_u32 s90, s38, s6
	s_addc_u32 s91, s39, 0
	s_add_u32 s94, s90, 0x20000
	s_addc_u32 s95, s91, 0
	s_lshl_b32 s6, s32, 2
	s_add_u32 s92, s22, s6
	s_addc_u32 s93, s23, 0
	v_mov_b32_e32 v227, v205
	v_mov_b32_e32 v228, v206
	s_branch .Ls5b_nx_done
.Ls5b_nx_s:
	s_sub_i32 s4, s83, 0x800
	s_lshr_b32 s4, s4, 3
	s_lshl_b32 s4, s4, 3
	s_add_i32 s32, s4, 0x4000
	s_lshl_b32 s6, s32, 12
	s_add_u32 s90, s38, s6
	s_addc_u32 s91, s39, 0
	s_add_u32 s94, s90, 0x20000
	s_addc_u32 s95, s91, 0
	s_lshl_b32 s6, s32, 2
	s_add_u32 s92, s22, s6
	s_addc_u32 s93, s23, 0
	v_mov_b32_e32 v227, v225
	v_mov_b32_e32 v228, v226
.Ls5b_nx_done:
	s_cmp_lg_u32 s35, 0
	s_cbranch_scc1 .Ls5b_cin_s
	s_cmp_lg_u32 s46, s98
	s_cbranch_scc1 .Ls5b_car_reset
	s_cmp_lt_i32 s52, s99
	s_cbranch_scc0 .Ls5b_car_ok
.Ls5b_car_reset:
	s_mov_b32 s98, s46
	s_mov_b32 s99, 0
	v_mov_b32_e32 v22, 0
	v_mov_b32_e32 v23, 0
.Ls5b_car_ok:
	s_lshl_b32 s4, s46, 22
	s_add_u32 s86, s28, s4
	s_addc_u32 s87, s29, 0
	s_add_i32 s57, s52, -1
.Ls5b_car_loop:
	s_cmp_ge_i32 s99, s52
	s_cbranch_scc1 .Ls5b_car_done
	s_add_i32 s4, s99, 0
	s_min_i32 s4, s4, s57
	s_lshl_b32 s4, s4, 15
	s_add_u32 s6, s86, s4
	s_addc_u32 s7, s87, 0
	global_load_dwordx2 v[64:65], v207, s[6:7]
	s_add_i32 s4, s99, 1
	s_min_i32 s4, s4, s57
	s_lshl_b32 s4, s4, 15
	s_add_u32 s6, s86, s4
	s_addc_u32 s7, s87, 0
	global_load_dwordx2 v[66:67], v207, s[6:7]
	s_add_i32 s4, s99, 2
	s_min_i32 s4, s4, s57
	s_lshl_b32 s4, s4, 15
	s_add_u32 s6, s86, s4
	s_addc_u32 s7, s87, 0
	global_load_dwordx2 v[68:69], v207, s[6:7]
	s_add_i32 s4, s99, 3
	s_min_i32 s4, s4, s57
	s_lshl_b32 s4, s4, 15
	s_add_u32 s6, s86, s4
	s_addc_u32 s7, s87, 0
	global_load_dwordx2 v[70:71], v207, s[6:7]
	s_add_i32 s4, s99, 4
	s_min_i32 s4, s4, s57
	s_lshl_b32 s4, s4, 15
	s_add_u32 s6, s86, s4
	s_addc_u32 s7, s87, 0
	global_load_dwordx2 v[72:73], v207, s[6:7]
	s_add_i32 s4, s99, 5
	s_min_i32 s4, s4, s57
	s_lshl_b32 s4, s4, 15
	s_add_u32 s6, s86, s4
	s_addc_u32 s7, s87, 0
	global_load_dwordx2 v[74:75], v207, s[6:7]
	s_add_i32 s4, s99, 6
	s_min_i32 s4, s4, s57
	s_lshl_b32 s4, s4, 15
	s_add_u32 s6, s86, s4
	s_addc_u32 s7, s87, 0
	global_load_dwordx2 v[76:77], v207, s[6:7]
	s_add_i32 s4, s99, 7
	s_min_i32 s4, s4, s57
	s_lshl_b32 s4, s4, 15
	s_add_u32 s6, s86, s4
	s_addc_u32 s7, s87, 0
	global_load_dwordx2 v[78:79], v207, s[6:7]
	s_add_i32 s4, s99, 8
	s_min_i32 s4, s4, s57
	s_lshl_b32 s4, s4, 15
	s_add_u32 s6, s86, s4
	s_addc_u32 s7, s87, 0
	global_load_dwordx2 v[80:81], v207, s[6:7]
	s_add_i32 s4, s99, 9
	s_min_i32 s4, s4, s57
	s_lshl_b32 s4, s4, 15
	s_add_u32 s6, s86, s4
	s_addc_u32 s7, s87, 0
	global_load_dwordx2 v[82:83], v207, s[6:7]
	s_add_i32 s4, s99, 10
	s_min_i32 s4, s4, s57
	s_lshl_b32 s4, s4, 15
	s_add_u32 s6, s86, s4
	s_addc_u32 s7, s87, 0
	global_load_dwordx2 v[84:85], v207, s[6:7]
	s_add_i32 s4, s99, 11
	s_min_i32 s4, s4, s57
	s_lshl_b32 s4, s4, 15
	s_add_u32 s6, s86, s4
	s_addc_u32 s7, s87, 0
	global_load_dwordx2 v[86:87], v207, s[6:7]
	s_add_i32 s4, s99, 12
	s_min_i32 s4, s4, s57
	s_lshl_b32 s4, s4, 15
	s_add_u32 s6, s86, s4
	s_addc_u32 s7, s87, 0
	global_load_dwordx2 v[88:89], v207, s[6:7]
	s_add_i32 s4, s99, 13
	s_min_i32 s4, s4, s57
	s_lshl_b32 s4, s4, 15
	s_add_u32 s6, s86, s4
	s_addc_u32 s7, s87, 0
	global_load_dwordx2 v[90:91], v207, s[6:7]
	s_add_i32 s4, s99, 14
	s_min_i32 s4, s4, s57
	s_lshl_b32 s4, s4, 15
	s_add_u32 s6, s86, s4
	s_addc_u32 s7, s87, 0
	global_load_dwordx2 v[92:93], v207, s[6:7]
	s_add_i32 s4, s99, 15
	s_min_i32 s4, s4, s57
	s_lshl_b32 s4, s4, 15
	s_add_u32 s6, s86, s4
	s_addc_u32 s7, s87, 0
	global_load_dwordx2 v[94:95], v207, s[6:7]
	s_waitcnt vmcnt(0)
	v_fma_f32 v168, v22, v18, v64
	v_fma_f32 v169, v22, v19, v65
	v_fma_f32 v22, -v23, v19, v168
	v_fma_f32 v23, v23, v18, v169
	s_add_i32 s4, s99, 1
	s_cmp_ge_i32 s4, s52
	s_cbranch_scc1 .Ls5b_car_grp
	v_fma_f32 v168, v22, v18, v66
	v_fma_f32 v169, v22, v19, v67
	v_fma_f32 v22, -v23, v19, v168
	v_fma_f32 v23, v23, v18, v169
	s_add_i32 s4, s99, 2
	s_cmp_ge_i32 s4, s52
	s_cbranch_scc1 .Ls5b_car_grp
	v_fma_f32 v168, v22, v18, v68
	v_fma_f32 v169, v22, v19, v69
	v_fma_f32 v22, -v23, v19, v168
	v_fma_f32 v23, v23, v18, v169
	s_add_i32 s4, s99, 3
	s_cmp_ge_i32 s4, s52
	s_cbranch_scc1 .Ls5b_car_grp
	v_fma_f32 v168, v22, v18, v70
	v_fma_f32 v169, v22, v19, v71
	v_fma_f32 v22, -v23, v19, v168
	v_fma_f32 v23, v23, v18, v169
	s_add_i32 s4, s99, 4
	s_cmp_ge_i32 s4, s52
	s_cbranch_scc1 .Ls5b_car_grp
	v_fma_f32 v168, v22, v18, v72
	v_fma_f32 v169, v22, v19, v73
	v_fma_f32 v22, -v23, v19, v168
	v_fma_f32 v23, v23, v18, v169
	s_add_i32 s4, s99, 5
	s_cmp_ge_i32 s4, s52
	s_cbranch_scc1 .Ls5b_car_grp
	v_fma_f32 v168, v22, v18, v74
	v_fma_f32 v169, v22, v19, v75
	v_fma_f32 v22, -v23, v19, v168
	v_fma_f32 v23, v23, v18, v169
	s_add_i32 s4, s99, 6
	s_cmp_ge_i32 s4, s52
	s_cbranch_scc1 .Ls5b_car_grp
	v_fma_f32 v168, v22, v18, v76
	v_fma_f32 v169, v22, v19, v77
	v_fma_f32 v22, -v23, v19, v168
	v_fma_f32 v23, v23, v18, v169
	s_add_i32 s4, s99, 7
	s_cmp_ge_i32 s4, s52
	s_cbranch_scc1 .Ls5b_car_grp
	v_fma_f32 v168, v22, v18, v78
	v_fma_f32 v169, v22, v19, v79
	v_fma_f32 v22, -v23, v19, v168
	v_fma_f32 v23, v23, v18, v169
	s_add_i32 s4, s99, 8
	s_cmp_ge_i32 s4, s52
	s_cbranch_scc1 .Ls5b_car_grp
	v_fma_f32 v168, v22, v18, v80
	v_fma_f32 v169, v22, v19, v81
	v_fma_f32 v22, -v23, v19, v168
	v_fma_f32 v23, v23, v18, v169
	s_add_i32 s4, s99, 9
	s_cmp_ge_i32 s4, s52
	s_cbranch_scc1 .Ls5b_car_grp
	v_fma_f32 v168, v22, v18, v82
	v_fma_f32 v169, v22, v19, v83
	v_fma_f32 v22, -v23, v19, v168
	v_fma_f32 v23, v23, v18, v169
	s_add_i32 s4, s99, 10
	s_cmp_ge_i32 s4, s52
	s_cbranch_scc1 .Ls5b_car_grp
	v_fma_f32 v168, v22, v18, v84
	v_fma_f32 v169, v22, v19, v85
	v_fma_f32 v22, -v23, v19, v168
	v_fma_f32 v23, v23, v18, v169
	s_add_i32 s4, s99, 11
	s_cmp_ge_i32 s4, s52
	s_cbranch_scc1 .Ls5b_car_grp
	v_fma_f32 v168, v22, v18, v86
	v_fma_f32 v169, v22, v19, v87
	v_fma_f32 v22, -v23, v19, v168
	v_fma_f32 v23, v23, v18, v169
	s_add_i32 s4, s99, 12
	s_cmp_ge_i32 s4, s52
	s_cbranch_scc1 .Ls5b_car_grp
	v_fma_f32 v168, v22, v18, v88
	v_fma_f32 v169, v22, v19, v89
	v_fma_f32 v22, -v23, v19, v168
	v_fma_f32 v23, v23, v18, v169
	s_add_i32 s4, s99, 13
	s_cmp_ge_i32 s4, s52
	s_cbranch_scc1 .Ls5b_car_grp
	v_fma_f32 v168, v22, v18, v90
	v_fma_f32 v169, v22, v19, v91
	v_fma_f32 v22, -v23, v19, v168
	v_fma_f32 v23, v23, v18, v169
	s_add_i32 s4, s99, 14
	s_cmp_ge_i32 s4, s52
	s_cbranch_scc1 .Ls5b_car_grp
	v_fma_f32 v168, v22, v18, v92
	v_fma_f32 v169, v22, v19, v93
	v_fma_f32 v22, -v23, v19, v168
	v_fma_f32 v23, v23, v18, v169
	s_add_i32 s4, s99, 15
	s_cmp_ge_i32 s4, s52
	s_cbranch_scc1 .Ls5b_car_grp
	v_fma_f32 v168, v22, v18, v94
	v_fma_f32 v169, v22, v19, v95
	v_fma_f32 v22, -v23, v19, v168
	v_fma_f32 v23, v23, v18, v169
.Ls5b_car_grp:
	s_add_i32 s99, s99, 16
	s_branch .Ls5b_car_loop
.Ls5b_car_done:
	s_mov_b32 s99, s52
	v_mov_b32_e32 v128, v22
	v_mov_b32_e32 v129, v23
	v_mov_b32_e32 v130, v22
	v_mov_b32_e32 v131, v23
	s_branch .Ls5b_cin_done
.Ls5b_cin_s:
	s_lshl_b32 s4, s46, 15
	s_add_u32 s6, s16, s4
	s_addc_u32 s7, s17, 0
	global_load_dwordx2 v[64:65], v207, s[6:7]
	s_waitcnt vmcnt(0)
	v_mov_b32_e32 v128, v64
	v_mov_b32_e32 v129, v65
	v_mov_b32_e32 v130, v64
	v_mov_b32_e32 v131, v65
.Ls5b_cin_done:
	s_nop 1
	v_permlane32_swap_b32_e32 v128, v130
	v_permlane32_swap_b32_e32 v129, v131
	s_waitcnt vmcnt(0)
	s_add_i32 s4, s31, 0
	s_lshl_b32 s4, s4, 11
	s_add_u32 s86, s12, s4
	s_addc_u32 s87, s13, 0
	s_add_u32 s88, s86, 0x8000
	s_addc_u32 s89, s87, 0
	v_fmamk_f32 v56, v194, 0x3a800000, v254
	v_rsq_f32_e32 v56, v56
	s_nop 0
	v_pk_mul_f32 v[148:149], v[178:179], v[56:57] op_sel_hi:[1,0]
	v_pk_mul_f32 v[150:151], v[180:181], v[56:57] op_sel_hi:[1,0]
	v_pk_mul_f32 v[152:153], v[182:183], v[56:57] op_sel_hi:[1,0]
	v_pk_mul_f32 v[154:155], v[184:185], v[56:57] op_sel_hi:[1,0]
	v_pk_mul_f32 v[148:149], v[140:141], v[148:149]
	v_pk_mul_f32 v[150:151], v[142:143], v[150:151]
	v_pk_mul_f32 v[152:153], v[144:145], v[152:153]
	v_pk_mul_f32 v[154:155], v[146:147], v[154:155]
	global_load_dwordx4 v[178:181], v227, s[90:91]
	global_load_dwordx4 v[182:185], v227, s[90:91] offset:16
	global_load_dword v194, v228, s[92:93]
	ds_write_b128 v231, v[148:151]
	ds_write_b128 v231, v[152:155] offset:16
	s_nop 1
	v_mfma_f32_32x32x2_f32 v[64:79], v148, v24, 0
	v_mfma_f32_32x32x2_f32 v[80:95], v148, v32, 0
	v_mfma_f32_32x32x2_f32 v[96:111], v148, v40, 0
	v_mfma_f32_32x32x2_f32 v[112:127], v148, v48, 0
	v_mfma_f32_32x32x2_f32 v[64:79], v149, v25, v[64:79]
	v_mfma_f32_32x32x2_f32 v[80:95], v149, v33, v[80:95]
	v_mfma_f32_32x32x2_f32 v[96:111], v149, v41, v[96:111]
	v_mfma_f32_32x32x2_f32 v[112:127], v149, v49, v[112:127]
	v_mfma_f32_32x32x2_f32 v[64:79], v150, v26, v[64:79]
	v_mfma_f32_32x32x2_f32 v[80:95], v150, v34, v[80:95]
	v_mfma_f32_32x32x2_f32 v[96:111], v150, v42, v[96:111]
	v_mfma_f32_32x32x2_f32 v[112:127], v150, v50, v[112:127]
	v_mfma_f32_32x32x2_f32 v[64:79], v151, v27, v[64:79]
	v_mfma_f32_32x32x2_f32 v[80:95], v151, v35, v[80:95]
	v_mfma_f32_32x32x2_f32 v[96:111], v151, v43, v[96:111]
	v_mfma_f32_32x32x2_f32 v[112:127], v151, v51, v[112:127]
	v_mfma_f32_32x32x2_f32 v[64:79], v152, v28, v[64:79]
	v_mfma_f32_32x32x2_f32 v[80:95], v152, v36, v[80:95]
	v_mfma_f32_32x32x2_f32 v[96:111], v152, v44, v[96:111]
	v_mfma_f32_32x32x2_f32 v[112:127], v152, v52, v[112:127]
	v_mfma_f32_32x32x2_f32 v[64:79], v153, v29, v[64:79]
	v_mfma_f32_32x32x2_f32 v[80:95], v153, v37, v[80:95]
	v_mfma_f32_32x32x2_f32 v[96:111], v153, v45, v[96:111]
	v_mfma_f32_32x32x2_f32 v[112:127], v153, v53, v[112:127]
	v_mfma_f32_32x32x2_f32 v[64:79], v154, v30, v[64:79]
	v_mfma_f32_32x32x2_f32 v[80:95], v154, v38, v[80:95]
	v_mfma_f32_32x32x2_f32 v[96:111], v154, v46, v[96:111]
	v_mfma_f32_32x32x2_f32 v[112:127], v154, v54, v[112:127]
	v_mfma_f32_32x32x2_f32 v[64:79], v155, v31, v[64:79]
	v_mfma_f32_32x32x2_f32 v[80:95], v155, v39, v[80:95]
	v_mfma_f32_32x32x2_f32 v[96:111], v155, v47, v[96:111]
	v_mfma_f32_32x32x2_f32 v[112:127], v155, v55, v[112:127]
	s_nop 7
	s_nop 7
	s_nop 1
	v_fma_f32 v168, v64, v0, v65
	v_fma_f32 v169, v64, v4, v81
	v_fma_f32 v65, -v80, v4, v168
	v_fma_f32 v81, v80, v0, v169
	v_fma_f32 v170, v96, v8, v97
	v_fma_f32 v171, v96, v14, v113
	v_fma_f32 v97, -v112, v14, v170
	v_fma_f32 v113, v112, v8, v171
	v_fma_f32 v168, v68, v0, v69
	v_fma_f32 v169, v68, v4, v85
	v_fma_f32 v69, -v84, v4, v168
	v_fma_f32 v85, v84, v0, v169
	v_fma_f32 v170, v100, v8, v101
	v_fma_f32 v171, v100, v14, v117
	v_fma_f32 v101, -v116, v14, v170
	v_fma_f32 v117, v116, v8, v171
	v_fma_f32 v168, v72, v0, v73
	v_fma_f32 v169, v72, v4, v89
	v_fma_f32 v73, -v88, v4, v168
	v_fma_f32 v89, v88, v0, v169
	v_fma_f32 v170, v104, v8, v105
	v_fma_f32 v171, v104, v14, v121
	v_fma_f32 v105, -v120, v14, v170
	v_fma_f32 v121, v120, v8, v171
	v_fma_f32 v168, v76, v0, v77
	v_fma_f32 v169, v76, v4, v93
	v_fma_f32 v77, -v92, v4, v168
	v_fma_f32 v93, v92, v0, v169
	v_fma_f32 v170, v108, v8, v109
	v_fma_f32 v171, v108, v14, v125
	v_fma_f32 v109, -v124, v14, v170
	v_fma_f32 v125, v124, v8, v171
	v_fma_f32 v168, v65, v0, v66
	v_fma_f32 v169, v65, v4, v82
	v_fma_f32 v66, -v81, v4, v168
	v_fma_f32 v82, v81, v0, v169
	v_fma_f32 v170, v97, v8, v98
	v_fma_f32 v171, v97, v14, v114
	v_fma_f32 v98, -v113, v14, v170
	v_fma_f32 v114, v113, v8, v171
	v_fma_f32 v168, v69, v0, v70
	v_fma_f32 v169, v69, v4, v86
	v_fma_f32 v70, -v85, v4, v168
	v_fma_f32 v86, v85, v0, v169
	v_fma_f32 v170, v101, v8, v102
	v_fma_f32 v171, v101, v14, v118
	v_fma_f32 v102, -v117, v14, v170
	v_fma_f32 v118, v117, v8, v171
	v_fma_f32 v168, v73, v0, v74
	v_fma_f32 v169, v73, v4, v90
	v_fma_f32 v74, -v89, v4, v168
	v_fma_f32 v90, v89, v0, v169
	v_fma_f32 v170, v105, v8, v106
	v_fma_f32 v171, v105, v14, v122
	v_fma_f32 v106, -v121, v14, v170
	v_fma_f32 v122, v121, v8, v171
	v_fma_f32 v168, v77, v0, v78
	v_fma_f32 v169, v77, v4, v94
	v_fma_f32 v78, -v93, v4, v168
	v_fma_f32 v94, v93, v0, v169
	v_fma_f32 v170, v109, v8, v110
	v_fma_f32 v171, v109, v14, v126
	v_fma_f32 v110, -v125, v14, v170
	v_fma_f32 v126, v125, v8, v171
	v_fma_f32 v168, v66, v0, v67
	v_fma_f32 v169, v66, v4, v83
	v_fma_f32 v67, -v82, v4, v168
	v_fma_f32 v83, v82, v0, v169
	v_fma_f32 v170, v98, v8, v99
	v_fma_f32 v171, v98, v14, v115
	v_fma_f32 v99, -v114, v14, v170
	v_fma_f32 v115, v114, v8, v171
	v_fma_f32 v168, v70, v0, v71
	v_fma_f32 v169, v70, v4, v87
	v_fma_f32 v71, -v86, v4, v168
	v_fma_f32 v87, v86, v0, v169
	v_fma_f32 v170, v102, v8, v103
	v_fma_f32 v171, v102, v14, v119
	v_fma_f32 v103, -v118, v14, v170
	v_fma_f32 v119, v118, v8, v171
	v_fma_f32 v168, v74, v0, v75
	v_fma_f32 v169, v74, v4, v91
	v_fma_f32 v75, -v90, v4, v168
	v_fma_f32 v91, v90, v0, v169
	v_fma_f32 v170, v106, v8, v107
	v_fma_f32 v171, v106, v14, v123
	v_fma_f32 v107, -v122, v14, v170
	v_fma_f32 v123, v122, v8, v171
	v_fma_f32 v168, v78, v0, v79
	v_fma_f32 v169, v78, v4, v95
	v_fma_f32 v79, -v94, v4, v168
	v_fma_f32 v95, v94, v0, v169
	v_fma_f32 v170, v110, v8, v111
	v_fma_f32 v171, v110, v14, v127
	v_fma_f32 v111, -v126, v14, v170
	v_fma_f32 v127, v126, v8, v171
	v_mov_b32_e32 v158, v67
	v_mov_b32_e32 v160, v67
	v_mov_b32_e32 v159, v83
	v_mov_b32_e32 v161, v83
	v_mov_b32_e32 v164, v99
	v_mov_b32_e32 v166, v99
	v_mov_b32_e32 v165, v115
	v_mov_b32_e32 v167, v115
	s_nop 1
	v_permlane32_swap_b32_e32 v158, v160
	v_permlane32_swap_b32_e32 v159, v161
	v_permlane32_swap_b32_e32 v164, v166
	v_permlane32_swap_b32_e32 v165, v167
	v_fma_f32 v168, v128, v3, v158
	v_fma_f32 v169, v128, v7, v159
	v_fma_f32 v132, -v129, v7, v168
	v_fma_f32 v133, v129, v3, v169
	v_fma_f32 v170, v130, v11, v164
	v_fma_f32 v171, v130, v17, v165
	v_fma_f32 v134, -v131, v17, v170
	v_fma_f32 v135, v131, v11, v171
	v_cndmask_b32_e64 v136, v128, v132, s[8:9]
	v_cndmask_b32_e64 v137, v129, v133, s[8:9]
	v_cndmask_b32_e64 v156, v130, v134, s[8:9]
	v_cndmask_b32_e64 v157, v131, v135, s[8:9]
	v_fma_f32 v168, v132, v3, v160
	v_fma_f32 v169, v132, v7, v161
	v_fma_f32 v128, -v133, v7, v168
	v_fma_f32 v129, v133, v3, v169
	v_fma_f32 v170, v134, v11, v166
	v_fma_f32 v171, v134, v17, v167
	v_fma_f32 v130, -v135, v17, v170
	v_fma_f32 v131, v135, v11, v171
	v_mov_b32_e32 v246, v128
	v_mov_b32_e32 v247, v129
	v_mov_b32_e32 v248, v130
	v_mov_b32_e32 v249, v131
	v_pk_fma_f32 v[64:65], v[0:1], v[136:137], v[64:65] op_sel_hi:[1,0,1]
	v_pk_fma_f32 v[80:81], v[0:1], v[136:137], v[80:81] op_sel:[0,1,0]
	v_pk_fma_f32 v[64:65], v[4:5], v[136:137], v[64:65] op_sel:[0,1,0] neg_lo:[1,0,0] neg_hi:[1,0,0]
	v_pk_fma_f32 v[80:81], v[4:5], v[136:137], v[80:81] op_sel_hi:[1,0,1]
	v_pk_fma_f32 v[66:67], v[2:3], v[136:137], v[66:67] op_sel_hi:[1,0,1]
	v_pk_fma_f32 v[82:83], v[2:3], v[136:137], v[82:83] op_sel:[0,1,0]
	v_pk_fma_f32 v[66:67], v[6:7], v[136:137], v[66:67] op_sel:[0,1,0] neg_lo:[1,0,0] neg_hi:[1,0,0]
	v_pk_fma_f32 v[82:83], v[6:7], v[136:137], v[82:83] op_sel_hi:[1,0,1]
	v_pk_fma_f32 v[96:97], v[8:9], v[156:157], v[96:97] op_sel_hi:[1,0,1]
	v_pk_fma_f32 v[112:113], v[8:9], v[156:157], v[112:113] op_sel:[0,1,0]
	v_pk_fma_f32 v[96:97], v[14:15], v[156:157], v[96:97] op_sel:[0,1,0] neg_lo:[1,0,0] neg_hi:[1,0,0]
	v_pk_fma_f32 v[112:113], v[14:15], v[156:157], v[112:113] op_sel_hi:[1,0,1]
	v_pk_fma_f32 v[98:99], v[10:11], v[156:157], v[98:99] op_sel_hi:[1,0,1]
	v_pk_fma_f32 v[114:115], v[10:11], v[156:157], v[114:115] op_sel:[0,1,0]
	v_pk_fma_f32 v[98:99], v[16:17], v[156:157], v[98:99] op_sel:[0,1,0] neg_lo:[1,0,0] neg_hi:[1,0,0]
	v_pk_fma_f32 v[114:115], v[16:17], v[156:157], v[114:115] op_sel_hi:[1,0,1]
	v_mov_b32_e32 v158, v71
	v_mov_b32_e32 v160, v71
	v_mov_b32_e32 v159, v87
	v_mov_b32_e32 v161, v87
	v_mov_b32_e32 v164, v103
	v_mov_b32_e32 v166, v103
	v_mov_b32_e32 v165, v119
	v_mov_b32_e32 v167, v119
	s_nop 1
	v_permlane32_swap_b32_e32 v158, v160
	v_permlane32_swap_b32_e32 v159, v161
	v_permlane32_swap_b32_e32 v164, v166
	v_permlane32_swap_b32_e32 v165, v167
	v_fma_f32 v168, v128, v3, v158
	v_fma_f32 v169, v128, v7, v159
	v_fma_f32 v132, -v129, v7, v168
	v_fma_f32 v133, v129, v3, v169
	v_fma_f32 v170, v130, v11, v164
	v_fma_f32 v171, v130, v17, v165
	v_fma_f32 v134, -v131, v17, v170
	v_fma_f32 v135, v131, v11, v171
	v_cndmask_b32_e64 v136, v128, v132, s[8:9]
	v_cndmask_b32_e64 v137, v129, v133, s[8:9]
	v_cndmask_b32_e64 v156, v130, v134, s[8:9]
	v_cndmask_b32_e64 v157, v131, v135, s[8:9]
	v_fma_f32 v168, v132, v3, v160
	v_fma_f32 v169, v132, v7, v161
	v_fma_f32 v128, -v133, v7, v168
	v_fma_f32 v129, v133, v3, v169
	v_fma_f32 v170, v134, v11, v166
	v_fma_f32 v171, v134, v17, v167
	v_fma_f32 v130, -v135, v17, v170
	v_fma_f32 v131, v135, v11, v171
	v_pk_fma_f32 v[68:69], v[0:1], v[136:137], v[68:69] op_sel_hi:[1,0,1]
	v_pk_fma_f32 v[84:85], v[0:1], v[136:137], v[84:85] op_sel:[0,1,0]
	v_pk_fma_f32 v[68:69], v[4:5], v[136:137], v[68:69] op_sel:[0,1,0] neg_lo:[1,0,0] neg_hi:[1,0,0]
	v_pk_fma_f32 v[84:85], v[4:5], v[136:137], v[84:85] op_sel_hi:[1,0,1]
	v_pk_fma_f32 v[70:71], v[2:3], v[136:137], v[70:71] op_sel_hi:[1,0,1]
	v_pk_fma_f32 v[86:87], v[2:3], v[136:137], v[86:87] op_sel:[0,1,0]
	v_pk_fma_f32 v[70:71], v[6:7], v[136:137], v[70:71] op_sel:[0,1,0] neg_lo:[1,0,0] neg_hi:[1,0,0]
	v_pk_fma_f32 v[86:87], v[6:7], v[136:137], v[86:87] op_sel_hi:[1,0,1]
	v_pk_fma_f32 v[100:101], v[8:9], v[156:157], v[100:101] op_sel_hi:[1,0,1]
	v_pk_fma_f32 v[116:117], v[8:9], v[156:157], v[116:117] op_sel:[0,1,0]
	v_pk_fma_f32 v[100:101], v[14:15], v[156:157], v[100:101] op_sel:[0,1,0] neg_lo:[1,0,0] neg_hi:[1,0,0]
	v_pk_fma_f32 v[116:117], v[14:15], v[156:157], v[116:117] op_sel_hi:[1,0,1]
	v_pk_fma_f32 v[102:103], v[10:11], v[156:157], v[102:103] op_sel_hi:[1,0,1]
	v_pk_fma_f32 v[118:119], v[10:11], v[156:157], v[118:119] op_sel:[0,1,0]
	v_pk_fma_f32 v[102:103], v[16:17], v[156:157], v[102:103] op_sel:[0,1,0] neg_lo:[1,0,0] neg_hi:[1,0,0]
	v_pk_fma_f32 v[118:119], v[16:17], v[156:157], v[118:119] op_sel_hi:[1,0,1]
	v_mov_b32_e32 v158, v75
	v_mov_b32_e32 v160, v75
	v_mov_b32_e32 v159, v91
	v_mov_b32_e32 v161, v91
	v_mov_b32_e32 v164, v107
	v_mov_b32_e32 v166, v107
	v_mov_b32_e32 v165, v123
	v_mov_b32_e32 v167, v123
	s_nop 1
	v_permlane32_swap_b32_e32 v158, v160
	v_permlane32_swap_b32_e32 v159, v161
	v_permlane32_swap_b32_e32 v164, v166
	v_permlane32_swap_b32_e32 v165, v167
	v_fma_f32 v168, v128, v3, v158
	v_fma_f32 v169, v128, v7, v159
	v_fma_f32 v132, -v129, v7, v168
	v_fma_f32 v133, v129, v3, v169
	v_fma_f32 v170, v130, v11, v164
	v_fma_f32 v171, v130, v17, v165
	v_fma_f32 v134, -v131, v17, v170
	v_fma_f32 v135, v131, v11, v171
	v_cndmask_b32_e64 v136, v128, v132, s[8:9]
	v_cndmask_b32_e64 v137, v129, v133, s[8:9]
	v_cndmask_b32_e64 v156, v130, v134, s[8:9]
	v_cndmask_b32_e64 v157, v131, v135, s[8:9]
	v_fma_f32 v168, v132, v3, v160
	v_fma_f32 v169, v132, v7, v161
	v_fma_f32 v128, -v133, v7, v168
	v_fma_f32 v129, v133, v3, v169
	v_fma_f32 v170, v134, v11, v166
	v_fma_f32 v171, v134, v17, v167
	v_fma_f32 v130, -v135, v17, v170
	v_fma_f32 v131, v135, v11, v171
	v_pk_fma_f32 v[72:73], v[0:1], v[136:137], v[72:73] op_sel_hi:[1,0,1]
	v_pk_fma_f32 v[88:89], v[0:1], v[136:137], v[88:89] op_sel:[0,1,0]
	v_pk_fma_f32 v[72:73], v[4:5], v[136:137], v[72:73] op_sel:[0,1,0] neg_lo:[1,0,0] neg_hi:[1,0,0]
	v_pk_fma_f32 v[88:89], v[4:5], v[136:137], v[88:89] op_sel_hi:[1,0,1]
	v_pk_fma_f32 v[74:75], v[2:3], v[136:137], v[74:75] op_sel_hi:[1,0,1]
	v_pk_fma_f32 v[90:91], v[2:3], v[136:137], v[90:91] op_sel:[0,1,0]
	v_pk_fma_f32 v[74:75], v[6:7], v[136:137], v[74:75] op_sel:[0,1,0] neg_lo:[1,0,0] neg_hi:[1,0,0]
	v_pk_fma_f32 v[90:91], v[6:7], v[136:137], v[90:91] op_sel_hi:[1,0,1]
	v_pk_fma_f32 v[104:105], v[8:9], v[156:157], v[104:105] op_sel_hi:[1,0,1]
	v_pk_fma_f32 v[120:121], v[8:9], v[156:157], v[120:121] op_sel:[0,1,0]
	v_pk_fma_f32 v[104:105], v[14:15], v[156:157], v[104:105] op_sel:[0,1,0] neg_lo:[1,0,0] neg_hi:[1,0,0]
	v_pk_fma_f32 v[120:121], v[14:15], v[156:157], v[120:121] op_sel_hi:[1,0,1]
	v_pk_fma_f32 v[106:107], v[10:11], v[156:157], v[106:107] op_sel_hi:[1,0,1]
	v_pk_fma_f32 v[122:123], v[10:11], v[156:157], v[122:123] op_sel:[0,1,0]
	v_pk_fma_f32 v[106:107], v[16:17], v[156:157], v[106:107] op_sel:[0,1,0] neg_lo:[1,0,0] neg_hi:[1,0,0]
	v_pk_fma_f32 v[122:123], v[16:17], v[156:157], v[122:123] op_sel_hi:[1,0,1]
	v_mov_b32_e32 v158, v79
	v_mov_b32_e32 v160, v79
	v_mov_b32_e32 v159, v95
	v_mov_b32_e32 v161, v95
	v_mov_b32_e32 v164, v111
	v_mov_b32_e32 v166, v111
	v_mov_b32_e32 v165, v127
	v_mov_b32_e32 v167, v127
	s_nop 1
	v_permlane32_swap_b32_e32 v158, v160
	v_permlane32_swap_b32_e32 v159, v161
	v_permlane32_swap_b32_e32 v164, v166
	v_permlane32_swap_b32_e32 v165, v167
	v_fma_f32 v168, v128, v3, v158
	v_fma_f32 v169, v128, v7, v159
	v_fma_f32 v132, -v129, v7, v168
	v_fma_f32 v133, v129, v3, v169
	v_fma_f32 v170, v130, v11, v164
	v_fma_f32 v171, v130, v17, v165
	v_fma_f32 v134, -v131, v17, v170
	v_fma_f32 v135, v131, v11, v171
	v_cndmask_b32_e64 v136, v128, v132, s[8:9]
	v_cndmask_b32_e64 v137, v129, v133, s[8:9]
	v_cndmask_b32_e64 v156, v130, v134, s[8:9]
	v_cndmask_b32_e64 v157, v131, v135, s[8:9]
	v_fma_f32 v168, v132, v3, v160
	v_fma_f32 v169, v132, v7, v161
	v_fma_f32 v128, -v133, v7, v168
	v_fma_f32 v129, v133, v3, v169
	v_fma_f32 v170, v134, v11, v166
	v_fma_f32 v171, v134, v17, v167
	v_fma_f32 v130, -v135, v17, v170
	v_fma_f32 v131, v135, v11, v171
	v_pk_fma_f32 v[76:77], v[0:1], v[136:137], v[76:77] op_sel_hi:[1,0,1]
	v_pk_fma_f32 v[92:93], v[0:1], v[136:137], v[92:93] op_sel:[0,1,0]
	v_pk_fma_f32 v[76:77], v[4:5], v[136:137], v[76:77] op_sel:[0,1,0] neg_lo:[1,0,0] neg_hi:[1,0,0]
	v_pk_fma_f32 v[92:93], v[4:5], v[136:137], v[92:93] op_sel_hi:[1,0,1]
	v_pk_fma_f32 v[78:79], v[2:3], v[136:137], v[78:79] op_sel_hi:[1,0,1]
	v_pk_fma_f32 v[94:95], v[2:3], v[136:137], v[94:95] op_sel:[0,1,0]
	v_pk_fma_f32 v[78:79], v[6:7], v[136:137], v[78:79] op_sel:[0,1,0] neg_lo:[1,0,0] neg_hi:[1,0,0]
	v_pk_fma_f32 v[94:95], v[6:7], v[136:137], v[94:95] op_sel_hi:[1,0,1]
	v_pk_fma_f32 v[108:109], v[8:9], v[156:157], v[108:109] op_sel_hi:[1,0,1]
	v_pk_fma_f32 v[124:125], v[8:9], v[156:157], v[124:125] op_sel:[0,1,0]
	v_pk_fma_f32 v[108:109], v[14:15], v[156:157], v[108:109] op_sel:[0,1,0] neg_lo:[1,0,0] neg_hi:[1,0,0]
	v_pk_fma_f32 v[124:125], v[14:15], v[156:157], v[124:125] op_sel_hi:[1,0,1]
	v_pk_fma_f32 v[110:111], v[10:11], v[156:157], v[110:111] op_sel_hi:[1,0,1]
	v_pk_fma_f32 v[126:127], v[10:11], v[156:157], v[126:127] op_sel:[0,1,0]
	v_pk_fma_f32 v[110:111], v[16:17], v[156:157], v[110:111] op_sel:[0,1,0] neg_lo:[1,0,0] neg_hi:[1,0,0]
	v_pk_fma_f32 v[126:127], v[16:17], v[156:157], v[126:127] op_sel_hi:[1,0,1]
	v_cvt_pk_bf16_f32 v56, v64, v80
	ds_write_b32 v229, v56 offset:0
	v_cvt_pk_bf16_f32 v57, v96, v112
	ds_write_b32 v229, v57 offset:128
	v_cvt_pk_bf16_f32 v58, v65, v81
	ds_write_b32 v229, v58 offset:272
	v_cvt_pk_bf16_f32 v59, v97, v113
	ds_write_b32 v229, v59 offset:400
	v_cvt_pk_bf16_f32 v56, v66, v82
	ds_write_b32 v229, v56 offset:544
	v_cvt_pk_bf16_f32 v57, v98, v114
	ds_write_b32 v229, v57 offset:672
	v_cvt_pk_bf16_f32 v58, v67, v83
	ds_write_b32 v229, v58 offset:816
	v_cvt_pk_bf16_f32 v59, v99, v115
	ds_write_b32 v229, v59 offset:944
	v_cvt_pk_bf16_f32 v56, v68, v84
	ds_write_b32 v229, v56 offset:2176
	v_cvt_pk_bf16_f32 v57, v100, v116
	ds_write_b32 v229, v57 offset:2304
	v_cvt_pk_bf16_f32 v58, v69, v85
	ds_write_b32 v229, v58 offset:2448
	v_cvt_pk_bf16_f32 v59, v101, v117
	ds_write_b32 v229, v59 offset:2576
	v_cvt_pk_bf16_f32 v56, v70, v86
	ds_write_b32 v229, v56 offset:2720
	v_cvt_pk_bf16_f32 v57, v102, v118
	ds_write_b32 v229, v57 offset:2848
	v_cvt_pk_bf16_f32 v58, v71, v87
	ds_write_b32 v229, v58 offset:2992
	v_cvt_pk_bf16_f32 v59, v103, v119
	ds_write_b32 v229, v59 offset:3120
	v_cvt_pk_bf16_f32 v56, v72, v88
	ds_write_b32 v229, v56 offset:4352
	v_cvt_pk_bf16_f32 v57, v104, v120
	ds_write_b32 v229, v57 offset:4480
	v_cvt_pk_bf16_f32 v58, v73, v89
	ds_write_b32 v229, v58 offset:4624
	v_cvt_pk_bf16_f32 v59, v105, v121
	ds_write_b32 v229, v59 offset:4752
	v_cvt_pk_bf16_f32 v56, v74, v90
	ds_write_b32 v229, v56 offset:4896
	v_cvt_pk_bf16_f32 v57, v106, v122
	ds_write_b32 v229, v57 offset:5024
	v_cvt_pk_bf16_f32 v58, v75, v91
	ds_write_b32 v229, v58 offset:5168
	v_cvt_pk_bf16_f32 v59, v107, v123
	ds_write_b32 v229, v59 offset:5296
	v_cvt_pk_bf16_f32 v56, v76, v92
	ds_write_b32 v229, v56 offset:6528
	v_cvt_pk_bf16_f32 v57, v108, v124
	ds_write_b32 v229, v57 offset:6656
	v_cvt_pk_bf16_f32 v58, v77, v93
	ds_write_b32 v229, v58 offset:6800
	v_cvt_pk_bf16_f32 v59, v109, v125
	ds_write_b32 v229, v59 offset:6928
	v_cvt_pk_bf16_f32 v56, v78, v94
	ds_write_b32 v229, v56 offset:7072
	v_cvt_pk_bf16_f32 v57, v110, v126
	ds_write_b32 v229, v57 offset:7200
	v_cvt_pk_bf16_f32 v58, v79, v95
	ds_write_b32 v229, v58 offset:7344
	v_cvt_pk_bf16_f32 v59, v111, v127
	ds_write_b32 v229, v59 offset:7472
	ds_read_b128 v[164:167], v230 offset:0
	ds_read_b128 v[168:171], v230 offset:64
	ds_read_b128 v[156:159], v230 offset:128
	ds_read_b128 v[132:135], v230 offset:192
	ds_read_b32 v56, v232 offset:0
	ds_read_b32 v57, v232 offset:64
	ds_read_b32 v58, v232 offset:128
	ds_read_b32 v59, v232 offset:192
	s_waitcnt lgkmcnt(7)
	v_mfma_f32_16x16x32_bf16 v[250:253], v[164:167], v[208:211], 0
	s_waitcnt lgkmcnt(6)
	v_mfma_f32_16x16x32_bf16 v[250:253], v[168:171], v[212:215], v[250:253]
	s_waitcnt lgkmcnt(5)
	v_mfma_f32_16x16x32_bf16 v[250:253], v[156:159], v[216:219], v[250:253]
	s_waitcnt lgkmcnt(4)
	v_mfma_f32_16x16x32_bf16 v[250:253], v[132:135], v[220:223], v[250:253]
	s_waitcnt lgkmcnt(0)
	s_nop 7
	s_nop 1
	v_fma_f32 v250, v224, v56, v250
	v_fma_f32 v251, v224, v57, v251
	v_fma_f32 v252, v224, v58, v252
	v_fma_f32 v253, v224, v59, v253
	v_mul_f32_e32 v60, 0x3d372713, v250
	v_mul_f32_e32 v172, 0x3d372713, v251
	v_mul_f32_e32 v173, 0x3d372713, v252
	v_mul_f32_e32 v245, 0x3d372713, v253
	v_mul_f32_e32 v60, v250, v60
	v_mul_f32_e32 v172, v251, v172
	v_mul_f32_e32 v173, v252, v173
	v_mul_f32_e32 v245, v253, v245
	v_fma_f32 v60, v250, v60, v250
	v_fma_f32 v172, v251, v172, v251
	v_fma_f32 v173, v252, v173, v252
	v_fma_f32 v245, v253, v245, v253
	v_mul_f32_e32 v60, 0x3f4c422a, v60
	v_mul_f32_e32 v172, 0x3f4c422a, v172
	v_mul_f32_e32 v173, 0x3f4c422a, v173
	v_mul_f32_e32 v245, 0x3f4c422a, v245
	v_add_f32_e32 v60, v60, v60
	v_add_f32_e32 v172, v172, v172
	v_add_f32_e32 v173, v173, v173
	v_add_f32_e32 v245, v245, v245
	v_mul_f32_e32 v60, 0x3fb8aa3b, v60
	v_mul_f32_e32 v172, 0x3fb8aa3b, v172
	v_mul_f32_e32 v173, 0x3fb8aa3b, v173
	v_mul_f32_e32 v245, 0x3fb8aa3b, v245
	v_exp_f32_e32 v60, v60
	v_exp_f32_e32 v172, v172
	v_exp_f32_e32 v173, v173
	v_exp_f32_e32 v245, v245
	v_mul_f32_e32 v250, 0.5, v250
	v_mul_f32_e32 v251, 0.5, v251
	v_mul_f32_e32 v252, 0.5, v252
	v_mul_f32_e32 v253, 0.5, v253
	v_add_f32_e32 v60, 1.0, v60
	v_add_f32_e32 v172, 1.0, v172
	v_add_f32_e32 v173, 1.0, v173
	v_add_f32_e32 v245, 1.0, v245
	v_rcp_f32_e32 v60, v60
	v_rcp_f32_e32 v172, v172
	v_rcp_f32_e32 v173, v173
	v_rcp_f32_e32 v245, v245
	s_nop 0
	v_fma_f32 v60, v60, -2.0, 1.0
	v_fma_f32 v172, v172, -2.0, 1.0
	v_fma_f32 v173, v173, -2.0, 1.0
	v_fma_f32 v245, v245, -2.0, 1.0
	v_add_f32_e32 v60, 1.0, v60
	v_add_f32_e32 v172, 1.0, v172
	v_add_f32_e32 v173, 1.0, v173
	v_add_f32_e32 v245, 1.0, v245
	v_mul_f32_e32 v250, v250, v60
	v_mul_f32_e32 v251, v251, v172
	v_mul_f32_e32 v252, v252, v173
	v_mul_f32_e32 v253, v253, v245
	v_cvt_pk_bf16_f32 v250, v250, 0
	v_cvt_pk_bf16_f32 v251, v251, 0
	v_cvt_pk_bf16_f32 v252, v252, 0
	v_cvt_pk_bf16_f32 v253, v253, 0
	s_cmp_lg_u32 s35, 0
	s_cselect_b32 s4, 0, -1
	s_mov_b32 exec_hi, s4
	global_store_short v233, v250, s[86:87]
	global_store_short v241, v251, s[86:87]
	global_store_short v242, v252, s[86:87]
	global_store_short v243, v253, s[86:87]
	s_mov_b32 exec_hi, -1
	s_cmp_lg_u32 s35, 0
	s_cbranch_scc1 .Ls5b_ep_skip0
	ds_read_b128 v[164:167], v230 offset:4352
	ds_read_b128 v[168:171], v230 offset:4416
	ds_read_b128 v[156:159], v230 offset:4480
	ds_read_b128 v[132:135], v230 offset:4544
	ds_read_b32 v56, v232 offset:1024
	ds_read_b32 v57, v232 offset:1088
	ds_read_b32 v58, v232 offset:1152
	ds_read_b32 v59, v232 offset:1216
	s_waitcnt lgkmcnt(7)
	v_mfma_f32_16x16x32_bf16 v[250:253], v[164:167], v[208:211], 0
	s_waitcnt lgkmcnt(6)
	v_mfma_f32_16x16x32_bf16 v[250:253], v[168:171], v[212:215], v[250:253]
	s_waitcnt lgkmcnt(5)
	v_mfma_f32_16x16x32_bf16 v[250:253], v[156:159], v[216:219], v[250:253]
	s_waitcnt lgkmcnt(4)
	v_mfma_f32_16x16x32_bf16 v[250:253], v[132:135], v[220:223], v[250:253]
	s_waitcnt lgkmcnt(0)
	s_nop 7
	s_nop 1
	v_fma_f32 v250, v224, v56, v250
	v_fma_f32 v251, v224, v57, v251
	v_fma_f32 v252, v224, v58, v252
	v_fma_f32 v253, v224, v59, v253
	v_mul_f32_e32 v60, 0x3d372713, v250
	v_mul_f32_e32 v172, 0x3d372713, v251
	v_mul_f32_e32 v173, 0x3d372713, v252
	v_mul_f32_e32 v245, 0x3d372713, v253
	v_mul_f32_e32 v60, v250, v60
	v_mul_f32_e32 v172, v251, v172
	v_mul_f32_e32 v173, v252, v173
	v_mul_f32_e32 v245, v253, v245
	v_fma_f32 v60, v250, v60, v250
	v_fma_f32 v172, v251, v172, v251
	v_fma_f32 v173, v252, v173, v252
	v_fma_f32 v245, v253, v245, v253
	v_mul_f32_e32 v60, 0x3f4c422a, v60
	v_mul_f32_e32 v172, 0x3f4c422a, v172
	v_mul_f32_e32 v173, 0x3f4c422a, v173
	v_mul_f32_e32 v245, 0x3f4c422a, v245
	v_add_f32_e32 v60, v60, v60
	v_add_f32_e32 v172, v172, v172
	v_add_f32_e32 v173, v173, v173
	v_add_f32_e32 v245, v245, v245
	v_mul_f32_e32 v60, 0x3fb8aa3b, v60
	v_mul_f32_e32 v172, 0x3fb8aa3b, v172
	v_mul_f32_e32 v173, 0x3fb8aa3b, v173
	v_mul_f32_e32 v245, 0x3fb8aa3b, v245
	v_exp_f32_e32 v60, v60
	v_exp_f32_e32 v172, v172
	v_exp_f32_e32 v173, v173
	v_exp_f32_e32 v245, v245
	v_mul_f32_e32 v250, 0.5, v250
	v_mul_f32_e32 v251, 0.5, v251
	v_mul_f32_e32 v252, 0.5, v252
	v_mul_f32_e32 v253, 0.5, v253
	v_add_f32_e32 v60, 1.0, v60
	v_add_f32_e32 v172, 1.0, v172
	v_add_f32_e32 v173, 1.0, v173
	v_add_f32_e32 v245, 1.0, v245
	v_rcp_f32_e32 v60, v60
	v_rcp_f32_e32 v172, v172
	v_rcp_f32_e32 v173, v173
	v_rcp_f32_e32 v245, v245
	s_nop 0
	v_fma_f32 v60, v60, -2.0, 1.0
	v_fma_f32 v172, v172, -2.0, 1.0
	v_fma_f32 v173, v173, -2.0, 1.0
	v_fma_f32 v245, v245, -2.0, 1.0
	v_add_f32_e32 v60, 1.0, v60
	v_add_f32_e32 v172, 1.0, v172
	v_add_f32_e32 v173, 1.0, v173
	v_add_f32_e32 v245, 1.0, v245
	v_mul_f32_e32 v250, v250, v60
	v_mul_f32_e32 v251, v251, v172
	v_mul_f32_e32 v252, v252, v173
	v_mul_f32_e32 v253, v253, v245
	v_cvt_pk_bf16_f32 v250, v250, 0
	v_cvt_pk_bf16_f32 v251, v251, 0
	v_cvt_pk_bf16_f32 v252, v252, 0
	v_cvt_pk_bf16_f32 v253, v253, 0
	global_store_short v233, v250, s[88:89]
	global_store_short v241, v251, s[88:89]
	global_store_short v242, v252, s[88:89]
	global_store_short v243, v253, s[88:89]
.Ls5b_ep_skip0:
	s_cmp_lg_u32 s35, 0
	s_cbranch_scc1 .Ls5b_item_end
	s_add_i32 s4, s31, 32
	s_lshl_b32 s4, s4, 11
	s_add_u32 s86, s12, s4
	s_addc_u32 s87, s13, 0
	s_add_u32 s88, s86, 0x8000
	s_addc_u32 s89, s87, 0
	v_fmamk_f32 v56, v195, 0x3a800000, v254
	v_rsq_f32_e32 v56, v56
	s_nop 0
	v_pk_mul_f32 v[148:149], v[186:187], v[56:57] op_sel_hi:[1,0]
	v_pk_mul_f32 v[150:151], v[188:189], v[56:57] op_sel_hi:[1,0]
	v_pk_mul_f32 v[152:153], v[190:191], v[56:57] op_sel_hi:[1,0]
	v_pk_mul_f32 v[154:155], v[192:193], v[56:57] op_sel_hi:[1,0]
	v_pk_mul_f32 v[148:149], v[140:141], v[148:149]
	v_pk_mul_f32 v[150:151], v[142:143], v[150:151]
	v_pk_mul_f32 v[152:153], v[144:145], v[152:153]
	v_pk_mul_f32 v[154:155], v[146:147], v[154:155]
	global_load_dwordx4 v[186:189], v227, s[94:95]
	global_load_dwordx4 v[190:193], v227, s[94:95] offset:16
	global_load_dword v195, v228, s[92:93] offset:128
	ds_write_b128 v231, v[148:151]
	ds_write_b128 v231, v[152:155] offset:16
	s_nop 1
	v_mfma_f32_32x32x2_f32 v[64:79], v148, v24, 0
	v_mfma_f32_32x32x2_f32 v[80:95], v148, v32, 0
	v_mfma_f32_32x32x2_f32 v[96:111], v148, v40, 0
	v_mfma_f32_32x32x2_f32 v[112:127], v148, v48, 0
	v_mfma_f32_32x32x2_f32 v[64:79], v149, v25, v[64:79]
	v_mfma_f32_32x32x2_f32 v[80:95], v149, v33, v[80:95]
	v_mfma_f32_32x32x2_f32 v[96:111], v149, v41, v[96:111]
	v_mfma_f32_32x32x2_f32 v[112:127], v149, v49, v[112:127]
	v_mfma_f32_32x32x2_f32 v[64:79], v150, v26, v[64:79]
	v_mfma_f32_32x32x2_f32 v[80:95], v150, v34, v[80:95]
	v_mfma_f32_32x32x2_f32 v[96:111], v150, v42, v[96:111]
	v_mfma_f32_32x32x2_f32 v[112:127], v150, v50, v[112:127]
	v_mfma_f32_32x32x2_f32 v[64:79], v151, v27, v[64:79]
	v_mfma_f32_32x32x2_f32 v[80:95], v151, v35, v[80:95]
	v_mfma_f32_32x32x2_f32 v[96:111], v151, v43, v[96:111]
	v_mfma_f32_32x32x2_f32 v[112:127], v151, v51, v[112:127]
	v_mfma_f32_32x32x2_f32 v[64:79], v152, v28, v[64:79]
	v_mfma_f32_32x32x2_f32 v[80:95], v152, v36, v[80:95]
	v_mfma_f32_32x32x2_f32 v[96:111], v152, v44, v[96:111]
	v_mfma_f32_32x32x2_f32 v[112:127], v152, v52, v[112:127]
	v_mfma_f32_32x32x2_f32 v[64:79], v153, v29, v[64:79]
	v_mfma_f32_32x32x2_f32 v[80:95], v153, v37, v[80:95]
	v_mfma_f32_32x32x2_f32 v[96:111], v153, v45, v[96:111]
	v_mfma_f32_32x32x2_f32 v[112:127], v153, v53, v[112:127]
	v_mfma_f32_32x32x2_f32 v[64:79], v154, v30, v[64:79]
	v_mfma_f32_32x32x2_f32 v[80:95], v154, v38, v[80:95]
	v_mfma_f32_32x32x2_f32 v[96:111], v154, v46, v[96:111]
	v_mfma_f32_32x32x2_f32 v[112:127], v154, v54, v[112:127]
	v_mfma_f32_32x32x2_f32 v[64:79], v155, v31, v[64:79]
	v_mfma_f32_32x32x2_f32 v[80:95], v155, v39, v[80:95]
	v_mfma_f32_32x32x2_f32 v[96:111], v155, v47, v[96:111]
	v_mfma_f32_32x32x2_f32 v[112:127], v155, v55, v[112:127]
	s_nop 7
	s_nop 7
	s_nop 1
	v_fma_f32 v168, v64, v0, v65
	v_fma_f32 v169, v64, v4, v81
	v_fma_f32 v65, -v80, v4, v168
	v_fma_f32 v81, v80, v0, v169
	v_fma_f32 v170, v96, v8, v97
	v_fma_f32 v171, v96, v14, v113
	v_fma_f32 v97, -v112, v14, v170
	v_fma_f32 v113, v112, v8, v171
	v_fma_f32 v168, v68, v0, v69
	v_fma_f32 v169, v68, v4, v85
	v_fma_f32 v69, -v84, v4, v168
	v_fma_f32 v85, v84, v0, v169
	v_fma_f32 v170, v100, v8, v101
	v_fma_f32 v171, v100, v14, v117
	v_fma_f32 v101, -v116, v14, v170
	v_fma_f32 v117, v116, v8, v171
	v_fma_f32 v168, v72, v0, v73
	v_fma_f32 v169, v72, v4, v89
	v_fma_f32 v73, -v88, v4, v168
	v_fma_f32 v89, v88, v0, v169
	v_fma_f32 v170, v104, v8, v105
	v_fma_f32 v171, v104, v14, v121
	v_fma_f32 v105, -v120, v14, v170
	v_fma_f32 v121, v120, v8, v171
	v_fma_f32 v168, v76, v0, v77
	v_fma_f32 v169, v76, v4, v93
	v_fma_f32 v77, -v92, v4, v168
	v_fma_f32 v93, v92, v0, v169
	v_fma_f32 v170, v108, v8, v109
	v_fma_f32 v171, v108, v14, v125
	v_fma_f32 v109, -v124, v14, v170
	v_fma_f32 v125, v124, v8, v171
	v_fma_f32 v168, v65, v0, v66
	v_fma_f32 v169, v65, v4, v82
	v_fma_f32 v66, -v81, v4, v168
	v_fma_f32 v82, v81, v0, v169
	v_fma_f32 v170, v97, v8, v98
	v_fma_f32 v171, v97, v14, v114
	v_fma_f32 v98, -v113, v14, v170
	v_fma_f32 v114, v113, v8, v171
	v_fma_f32 v168, v69, v0, v70
	v_fma_f32 v169, v69, v4, v86
	v_fma_f32 v70, -v85, v4, v168
	v_fma_f32 v86, v85, v0, v169
	v_fma_f32 v170, v101, v8, v102
	v_fma_f32 v171, v101, v14, v118
	v_fma_f32 v102, -v117, v14, v170
	v_fma_f32 v118, v117, v8, v171
	v_fma_f32 v168, v73, v0, v74
	v_fma_f32 v169, v73, v4, v90
	v_fma_f32 v74, -v89, v4, v168
	v_fma_f32 v90, v89, v0, v169
	v_fma_f32 v170, v105, v8, v106
	v_fma_f32 v171, v105, v14, v122
	v_fma_f32 v106, -v121, v14, v170
	v_fma_f32 v122, v121, v8, v171
	v_fma_f32 v168, v77, v0, v78
	v_fma_f32 v169, v77, v4, v94
	v_fma_f32 v78, -v93, v4, v168
	v_fma_f32 v94, v93, v0, v169
	v_fma_f32 v170, v109, v8, v110
	v_fma_f32 v171, v109, v14, v126
	v_fma_f32 v110, -v125, v14, v170
	v_fma_f32 v126, v125, v8, v171
	v_fma_f32 v168, v66, v0, v67
	v_fma_f32 v169, v66, v4, v83
	v_fma_f32 v67, -v82, v4, v168
	v_fma_f32 v83, v82, v0, v169
	v_fma_f32 v170, v98, v8, v99
	v_fma_f32 v171, v98, v14, v115
	v_fma_f32 v99, -v114, v14, v170
	v_fma_f32 v115, v114, v8, v171
	v_fma_f32 v168, v70, v0, v71
	v_fma_f32 v169, v70, v4, v87
	v_fma_f32 v71, -v86, v4, v168
	v_fma_f32 v87, v86, v0, v169
	v_fma_f32 v170, v102, v8, v103
	v_fma_f32 v171, v102, v14, v119
	v_fma_f32 v103, -v118, v14, v170
	v_fma_f32 v119, v118, v8, v171
	v_fma_f32 v168, v74, v0, v75
	v_fma_f32 v169, v74, v4, v91
	v_fma_f32 v75, -v90, v4, v168
	v_fma_f32 v91, v90, v0, v169
	v_fma_f32 v170, v106, v8, v107
	v_fma_f32 v171, v106, v14, v123
	v_fma_f32 v107, -v122, v14, v170
	v_fma_f32 v123, v122, v8, v171
	v_fma_f32 v168, v78, v0, v79
	v_fma_f32 v169, v78, v4, v95
	v_fma_f32 v79, -v94, v4, v168
	v_fma_f32 v95, v94, v0, v169
	v_fma_f32 v170, v110, v8, v111
	v_fma_f32 v171, v110, v14, v127
	v_fma_f32 v111, -v126, v14, v170
	v_fma_f32 v127, v126, v8, v171
	v_mov_b32_e32 v158, v67
	v_mov_b32_e32 v160, v67
	v_mov_b32_e32 v159, v83
	v_mov_b32_e32 v161, v83
	v_mov_b32_e32 v164, v99
	v_mov_b32_e32 v166, v99
	v_mov_b32_e32 v165, v115
	v_mov_b32_e32 v167, v115
	s_nop 1
	v_permlane32_swap_b32_e32 v158, v160
	v_permlane32_swap_b32_e32 v159, v161
	v_permlane32_swap_b32_e32 v164, v166
	v_permlane32_swap_b32_e32 v165, v167
	v_fma_f32 v168, v128, v3, v158
	v_fma_f32 v169, v128, v7, v159
	v_fma_f32 v132, -v129, v7, v168
	v_fma_f32 v133, v129, v3, v169
	v_fma_f32 v170, v130, v11, v164
	v_fma_f32 v171, v130, v17, v165
	v_fma_f32 v134, -v131, v17, v170
	v_fma_f32 v135, v131, v11, v171
	v_cndmask_b32_e64 v136, v128, v132, s[8:9]
	v_cndmask_b32_e64 v137, v129, v133, s[8:9]
	v_cndmask_b32_e64 v156, v130, v134, s[8:9]
	v_cndmask_b32_e64 v157, v131, v135, s[8:9]
	v_fma_f32 v168, v132, v3, v160
	v_fma_f32 v169, v132, v7, v161
	v_fma_f32 v128, -v133, v7, v168
	v_fma_f32 v129, v133, v3, v169
	v_fma_f32 v170, v134, v11, v166
	v_fma_f32 v171, v134, v17, v167
	v_fma_f32 v130, -v135, v17, v170
	v_fma_f32 v131, v135, v11, v171
	v_mov_b32_e32 v246, v128
	v_mov_b32_e32 v247, v129
	v_mov_b32_e32 v248, v130
	v_mov_b32_e32 v249, v131
	v_pk_fma_f32 v[64:65], v[0:1], v[136:137], v[64:65] op_sel_hi:[1,0,1]
	v_pk_fma_f32 v[80:81], v[0:1], v[136:137], v[80:81] op_sel:[0,1,0]
	v_pk_fma_f32 v[64:65], v[4:5], v[136:137], v[64:65] op_sel:[0,1,0] neg_lo:[1,0,0] neg_hi:[1,0,0]
	v_pk_fma_f32 v[80:81], v[4:5], v[136:137], v[80:81] op_sel_hi:[1,0,1]
	v_pk_fma_f32 v[66:67], v[2:3], v[136:137], v[66:67] op_sel_hi:[1,0,1]
	v_pk_fma_f32 v[82:83], v[2:3], v[136:137], v[82:83] op_sel:[0,1,0]
	v_pk_fma_f32 v[66:67], v[6:7], v[136:137], v[66:67] op_sel:[0,1,0] neg_lo:[1,0,0] neg_hi:[1,0,0]
	v_pk_fma_f32 v[82:83], v[6:7], v[136:137], v[82:83] op_sel_hi:[1,0,1]
	v_pk_fma_f32 v[96:97], v[8:9], v[156:157], v[96:97] op_sel_hi:[1,0,1]
	v_pk_fma_f32 v[112:113], v[8:9], v[156:157], v[112:113] op_sel:[0,1,0]
	v_pk_fma_f32 v[96:97], v[14:15], v[156:157], v[96:97] op_sel:[0,1,0] neg_lo:[1,0,0] neg_hi:[1,0,0]
	v_pk_fma_f32 v[112:113], v[14:15], v[156:157], v[112:113] op_sel_hi:[1,0,1]
	v_pk_fma_f32 v[98:99], v[10:11], v[156:157], v[98:99] op_sel_hi:[1,0,1]
	v_pk_fma_f32 v[114:115], v[10:11], v[156:157], v[114:115] op_sel:[0,1,0]
	v_pk_fma_f32 v[98:99], v[16:17], v[156:157], v[98:99] op_sel:[0,1,0] neg_lo:[1,0,0] neg_hi:[1,0,0]
	v_pk_fma_f32 v[114:115], v[16:17], v[156:157], v[114:115] op_sel_hi:[1,0,1]
	v_mov_b32_e32 v158, v71
	v_mov_b32_e32 v160, v71
	v_mov_b32_e32 v159, v87
	v_mov_b32_e32 v161, v87
	v_mov_b32_e32 v164, v103
	v_mov_b32_e32 v166, v103
	v_mov_b32_e32 v165, v119
	v_mov_b32_e32 v167, v119
	s_nop 1
	v_permlane32_swap_b32_e32 v158, v160
	v_permlane32_swap_b32_e32 v159, v161
	v_permlane32_swap_b32_e32 v164, v166
	v_permlane32_swap_b32_e32 v165, v167
	v_fma_f32 v168, v128, v3, v158
	v_fma_f32 v169, v128, v7, v159
	v_fma_f32 v132, -v129, v7, v168
	v_fma_f32 v133, v129, v3, v169
	v_fma_f32 v170, v130, v11, v164
	v_fma_f32 v171, v130, v17, v165
	v_fma_f32 v134, -v131, v17, v170
	v_fma_f32 v135, v131, v11, v171
	v_cndmask_b32_e64 v136, v128, v132, s[8:9]
	v_cndmask_b32_e64 v137, v129, v133, s[8:9]
	v_cndmask_b32_e64 v156, v130, v134, s[8:9]
	v_cndmask_b32_e64 v157, v131, v135, s[8:9]
	v_fma_f32 v168, v132, v3, v160
	v_fma_f32 v169, v132, v7, v161
	v_fma_f32 v128, -v133, v7, v168
	v_fma_f32 v129, v133, v3, v169
	v_fma_f32 v170, v134, v11, v166
	v_fma_f32 v171, v134, v17, v167
	v_fma_f32 v130, -v135, v17, v170
	v_fma_f32 v131, v135, v11, v171
	v_pk_fma_f32 v[68:69], v[0:1], v[136:137], v[68:69] op_sel_hi:[1,0,1]
	v_pk_fma_f32 v[84:85], v[0:1], v[136:137], v[84:85] op_sel:[0,1,0]
	v_pk_fma_f32 v[68:69], v[4:5], v[136:137], v[68:69] op_sel:[0,1,0] neg_lo:[1,0,0] neg_hi:[1,0,0]
	v_pk_fma_f32 v[84:85], v[4:5], v[136:137], v[84:85] op_sel_hi:[1,0,1]
	v_pk_fma_f32 v[70:71], v[2:3], v[136:137], v[70:71] op_sel_hi:[1,0,1]
	v_pk_fma_f32 v[86:87], v[2:3], v[136:137], v[86:87] op_sel:[0,1,0]
	v_pk_fma_f32 v[70:71], v[6:7], v[136:137], v[70:71] op_sel:[0,1,0] neg_lo:[1,0,0] neg_hi:[1,0,0]
	v_pk_fma_f32 v[86:87], v[6:7], v[136:137], v[86:87] op_sel_hi:[1,0,1]
	v_pk_fma_f32 v[100:101], v[8:9], v[156:157], v[100:101] op_sel_hi:[1,0,1]
	v_pk_fma_f32 v[116:117], v[8:9], v[156:157], v[116:117] op_sel:[0,1,0]
	v_pk_fma_f32 v[100:101], v[14:15], v[156:157], v[100:101] op_sel:[0,1,0] neg_lo:[1,0,0] neg_hi:[1,0,0]
	v_pk_fma_f32 v[116:117], v[14:15], v[156:157], v[116:117] op_sel_hi:[1,0,1]
	v_pk_fma_f32 v[102:103], v[10:11], v[156:157], v[102:103] op_sel_hi:[1,0,1]
	v_pk_fma_f32 v[118:119], v[10:11], v[156:157], v[118:119] op_sel:[0,1,0]
	v_pk_fma_f32 v[102:103], v[16:17], v[156:157], v[102:103] op_sel:[0,1,0] neg_lo:[1,0,0] neg_hi:[1,0,0]
	v_pk_fma_f32 v[118:119], v[16:17], v[156:157], v[118:119] op_sel_hi:[1,0,1]
	v_mov_b32_e32 v158, v75
	v_mov_b32_e32 v160, v75
	v_mov_b32_e32 v159, v91
	v_mov_b32_e32 v161, v91
	v_mov_b32_e32 v164, v107
	v_mov_b32_e32 v166, v107
	v_mov_b32_e32 v165, v123
	v_mov_b32_e32 v167, v123
	s_nop 1
	v_permlane32_swap_b32_e32 v158, v160
	v_permlane32_swap_b32_e32 v159, v161
	v_permlane32_swap_b32_e32 v164, v166
	v_permlane32_swap_b32_e32 v165, v167
	v_fma_f32 v168, v128, v3, v158
	v_fma_f32 v169, v128, v7, v159
	v_fma_f32 v132, -v129, v7, v168
	v_fma_f32 v133, v129, v3, v169
	v_fma_f32 v170, v130, v11, v164
	v_fma_f32 v171, v130, v17, v165
	v_fma_f32 v134, -v131, v17, v170
	v_fma_f32 v135, v131, v11, v171
	v_cndmask_b32_e64 v136, v128, v132, s[8:9]
	v_cndmask_b32_e64 v137, v129, v133, s[8:9]
	v_cndmask_b32_e64 v156, v130, v134, s[8:9]
	v_cndmask_b32_e64 v157, v131, v135, s[8:9]
	v_fma_f32 v168, v132, v3, v160
	v_fma_f32 v169, v132, v7, v161
	v_fma_f32 v128, -v133, v7, v168
	v_fma_f32 v129, v133, v3, v169
	v_fma_f32 v170, v134, v11, v166
	v_fma_f32 v171, v134, v17, v167
	v_fma_f32 v130, -v135, v17, v170
	v_fma_f32 v131, v135, v11, v171
	v_pk_fma_f32 v[72:73], v[0:1], v[136:137], v[72:73] op_sel_hi:[1,0,1]
	v_pk_fma_f32 v[88:89], v[0:1], v[136:137], v[88:89] op_sel:[0,1,0]
	v_pk_fma_f32 v[72:73], v[4:5], v[136:137], v[72:73] op_sel:[0,1,0] neg_lo:[1,0,0] neg_hi:[1,0,0]
	v_pk_fma_f32 v[88:89], v[4:5], v[136:137], v[88:89] op_sel_hi:[1,0,1]
	v_pk_fma_f32 v[74:75], v[2:3], v[136:137], v[74:75] op_sel_hi:[1,0,1]
	v_pk_fma_f32 v[90:91], v[2:3], v[136:137], v[90:91] op_sel:[0,1,0]
	v_pk_fma_f32 v[74:75], v[6:7], v[136:137], v[74:75] op_sel:[0,1,0] neg_lo:[1,0,0] neg_hi:[1,0,0]
	v_pk_fma_f32 v[90:91], v[6:7], v[136:137], v[90:91] op_sel_hi:[1,0,1]
	v_pk_fma_f32 v[104:105], v[8:9], v[156:157], v[104:105] op_sel_hi:[1,0,1]
	v_pk_fma_f32 v[120:121], v[8:9], v[156:157], v[120:121] op_sel:[0,1,0]
	v_pk_fma_f32 v[104:105], v[14:15], v[156:157], v[104:105] op_sel:[0,1,0] neg_lo:[1,0,0] neg_hi:[1,0,0]
	v_pk_fma_f32 v[120:121], v[14:15], v[156:157], v[120:121] op_sel_hi:[1,0,1]
	v_pk_fma_f32 v[106:107], v[10:11], v[156:157], v[106:107] op_sel_hi:[1,0,1]
	v_pk_fma_f32 v[122:123], v[10:11], v[156:157], v[122:123] op_sel:[0,1,0]
	v_pk_fma_f32 v[106:107], v[16:17], v[156:157], v[106:107] op_sel:[0,1,0] neg_lo:[1,0,0] neg_hi:[1,0,0]
	v_pk_fma_f32 v[122:123], v[16:17], v[156:157], v[122:123] op_sel_hi:[1,0,1]
	v_mov_b32_e32 v158, v79
	v_mov_b32_e32 v160, v79
	v_mov_b32_e32 v159, v95
	v_mov_b32_e32 v161, v95
	v_mov_b32_e32 v164, v111
	v_mov_b32_e32 v166, v111
	v_mov_b32_e32 v165, v127
	v_mov_b32_e32 v167, v127
	s_nop 1
	v_permlane32_swap_b32_e32 v158, v160
	v_permlane32_swap_b32_e32 v159, v161
	v_permlane32_swap_b32_e32 v164, v166
	v_permlane32_swap_b32_e32 v165, v167
	v_fma_f32 v168, v128, v3, v158
	v_fma_f32 v169, v128, v7, v159
	v_fma_f32 v132, -v129, v7, v168
	v_fma_f32 v133, v129, v3, v169
	v_fma_f32 v170, v130, v11, v164
	v_fma_f32 v171, v130, v17, v165
	v_fma_f32 v134, -v131, v17, v170
	v_fma_f32 v135, v131, v11, v171
	v_cndmask_b32_e64 v136, v128, v132, s[8:9]
	v_cndmask_b32_e64 v137, v129, v133, s[8:9]
	v_cndmask_b32_e64 v156, v130, v134, s[8:9]
	v_cndmask_b32_e64 v157, v131, v135, s[8:9]
	v_fma_f32 v168, v132, v3, v160
	v_fma_f32 v169, v132, v7, v161
	v_fma_f32 v128, -v133, v7, v168
	v_fma_f32 v129, v133, v3, v169
	v_fma_f32 v170, v134, v11, v166
	v_fma_f32 v171, v134, v17, v167
	v_fma_f32 v130, -v135, v17, v170
	v_fma_f32 v131, v135, v11, v171
	v_pk_fma_f32 v[76:77], v[0:1], v[136:137], v[76:77] op_sel_hi:[1,0,1]
	v_pk_fma_f32 v[92:93], v[0:1], v[136:137], v[92:93] op_sel:[0,1,0]
	v_pk_fma_f32 v[76:77], v[4:5], v[136:137], v[76:77] op_sel:[0,1,0] neg_lo:[1,0,0] neg_hi:[1,0,0]
	v_pk_fma_f32 v[92:93], v[4:5], v[136:137], v[92:93] op_sel_hi:[1,0,1]
	v_pk_fma_f32 v[78:79], v[2:3], v[136:137], v[78:79] op_sel_hi:[1,0,1]
	v_pk_fma_f32 v[94:95], v[2:3], v[136:137], v[94:95] op_sel:[0,1,0]
	v_pk_fma_f32 v[78:79], v[6:7], v[136:137], v[78:79] op_sel:[0,1,0] neg_lo:[1,0,0] neg_hi:[1,0,0]
	v_pk_fma_f32 v[94:95], v[6:7], v[136:137], v[94:95] op_sel_hi:[1,0,1]
	v_pk_fma_f32 v[108:109], v[8:9], v[156:157], v[108:109] op_sel_hi:[1,0,1]
	v_pk_fma_f32 v[124:125], v[8:9], v[156:157], v[124:125] op_sel:[0,1,0]
	v_pk_fma_f32 v[108:109], v[14:15], v[156:157], v[108:109] op_sel:[0,1,0] neg_lo:[1,0,0] neg_hi:[1,0,0]
	v_pk_fma_f32 v[124:125], v[14:15], v[156:157], v[124:125] op_sel_hi:[1,0,1]
	v_pk_fma_f32 v[110:111], v[10:11], v[156:157], v[110:111] op_sel_hi:[1,0,1]
	v_pk_fma_f32 v[126:127], v[10:11], v[156:157], v[126:127] op_sel:[0,1,0]
	v_pk_fma_f32 v[110:111], v[16:17], v[156:157], v[110:111] op_sel:[0,1,0] neg_lo:[1,0,0] neg_hi:[1,0,0]
	v_pk_fma_f32 v[126:127], v[16:17], v[156:157], v[126:127] op_sel_hi:[1,0,1]
	v_cvt_pk_bf16_f32 v56, v64, v80
	ds_write_b32 v229, v56 offset:0
	v_cvt_pk_bf16_f32 v57, v96, v112
	ds_write_b32 v229, v57 offset:128
	v_cvt_pk_bf16_f32 v58, v65, v81
	ds_write_b32 v229, v58 offset:272
	v_cvt_pk_bf16_f32 v59, v97, v113
	ds_write_b32 v229, v59 offset:400
	v_cvt_pk_bf16_f32 v56, v66, v82
	ds_write_b32 v229, v56 offset:544
	v_cvt_pk_bf16_f32 v57, v98, v114
	ds_write_b32 v229, v57 offset:672
	v_cvt_pk_bf16_f32 v58, v67, v83
	ds_write_b32 v229, v58 offset:816
	v_cvt_pk_bf16_f32 v59, v99, v115
	ds_write_b32 v229, v59 offset:944
	v_cvt_pk_bf16_f32 v56, v68, v84
	ds_write_b32 v229, v56 offset:2176
	v_cvt_pk_bf16_f32 v57, v100, v116
	ds_write_b32 v229, v57 offset:2304
	v_cvt_pk_bf16_f32 v58, v69, v85
	ds_write_b32 v229, v58 offset:2448
	v_cvt_pk_bf16_f32 v59, v101, v117
	ds_write_b32 v229, v59 offset:2576
	v_cvt_pk_bf16_f32 v56, v70, v86
	ds_write_b32 v229, v56 offset:2720
	v_cvt_pk_bf16_f32 v57, v102, v118
	ds_write_b32 v229, v57 offset:2848
	v_cvt_pk_bf16_f32 v58, v71, v87
	ds_write_b32 v229, v58 offset:2992
	v_cvt_pk_bf16_f32 v59, v103, v119
	ds_write_b32 v229, v59 offset:3120
	v_cvt_pk_bf16_f32 v56, v72, v88
	ds_write_b32 v229, v56 offset:4352
	v_cvt_pk_bf16_f32 v57, v104, v120
	ds_write_b32 v229, v57 offset:4480
	v_cvt_pk_bf16_f32 v58, v73, v89
	ds_write_b32 v229, v58 offset:4624
	v_cvt_pk_bf16_f32 v59, v105, v121
	ds_write_b32 v229, v59 offset:4752
	v_cvt_pk_bf16_f32 v56, v74, v90
	ds_write_b32 v229, v56 offset:4896
	v_cvt_pk_bf16_f32 v57, v106, v122
	ds_write_b32 v229, v57 offset:5024
	v_cvt_pk_bf16_f32 v58, v75, v91
	ds_write_b32 v229, v58 offset:5168
	v_cvt_pk_bf16_f32 v59, v107, v123
	ds_write_b32 v229, v59 offset:5296
	v_cvt_pk_bf16_f32 v56, v76, v92
	ds_write_b32 v229, v56 offset:6528
	v_cvt_pk_bf16_f32 v57, v108, v124
	ds_write_b32 v229, v57 offset:6656
	v_cvt_pk_bf16_f32 v58, v77, v93
	ds_write_b32 v229, v58 offset:6800
	v_cvt_pk_bf16_f32 v59, v109, v125
	ds_write_b32 v229, v59 offset:6928
	v_cvt_pk_bf16_f32 v56, v78, v94
	ds_write_b32 v229, v56 offset:7072
	v_cvt_pk_bf16_f32 v57, v110, v126
	ds_write_b32 v229, v57 offset:7200
	v_cvt_pk_bf16_f32 v58, v79, v95
	ds_write_b32 v229, v58 offset:7344
	v_cvt_pk_bf16_f32 v59, v111, v127
	ds_write_b32 v229, v59 offset:7472
	ds_read_b128 v[164:167], v230 offset:0
	ds_read_b128 v[168:171], v230 offset:64
	ds_read_b128 v[156:159], v230 offset:128
	ds_read_b128 v[132:135], v230 offset:192
	ds_read_b32 v56, v232 offset:0
	ds_read_b32 v57, v232 offset:64
	ds_read_b32 v58, v232 offset:128
	ds_read_b32 v59, v232 offset:192
	s_waitcnt lgkmcnt(7)
	v_mfma_f32_16x16x32_bf16 v[250:253], v[164:167], v[208:211], 0
	s_waitcnt lgkmcnt(6)
	v_mfma_f32_16x16x32_bf16 v[250:253], v[168:171], v[212:215], v[250:253]
	s_waitcnt lgkmcnt(5)
	v_mfma_f32_16x16x32_bf16 v[250:253], v[156:159], v[216:219], v[250:253]
	s_waitcnt lgkmcnt(4)
	v_mfma_f32_16x16x32_bf16 v[250:253], v[132:135], v[220:223], v[250:253]
	s_waitcnt lgkmcnt(0)
	s_nop 7
	s_nop 1
	v_fma_f32 v250, v224, v56, v250
	v_fma_f32 v251, v224, v57, v251
	v_fma_f32 v252, v224, v58, v252
	v_fma_f32 v253, v224, v59, v253
	v_mul_f32_e32 v60, 0x3d372713, v250
	v_mul_f32_e32 v172, 0x3d372713, v251
	v_mul_f32_e32 v173, 0x3d372713, v252
	v_mul_f32_e32 v245, 0x3d372713, v253
	v_mul_f32_e32 v60, v250, v60
	v_mul_f32_e32 v172, v251, v172
	v_mul_f32_e32 v173, v252, v173
	v_mul_f32_e32 v245, v253, v245
	v_fma_f32 v60, v250, v60, v250
	v_fma_f32 v172, v251, v172, v251
	v_fma_f32 v173, v252, v173, v252
	v_fma_f32 v245, v253, v245, v253
	v_mul_f32_e32 v60, 0x3f4c422a, v60
	v_mul_f32_e32 v172, 0x3f4c422a, v172
	v_mul_f32_e32 v173, 0x3f4c422a, v173
	v_mul_f32_e32 v245, 0x3f4c422a, v245
	v_add_f32_e32 v60, v60, v60
	v_add_f32_e32 v172, v172, v172
	v_add_f32_e32 v173, v173, v173
	v_add_f32_e32 v245, v245, v245
	v_mul_f32_e32 v60, 0x3fb8aa3b, v60
	v_mul_f32_e32 v172, 0x3fb8aa3b, v172
	v_mul_f32_e32 v173, 0x3fb8aa3b, v173
	v_mul_f32_e32 v245, 0x3fb8aa3b, v245
	v_exp_f32_e32 v60, v60
	v_exp_f32_e32 v172, v172
	v_exp_f32_e32 v173, v173
	v_exp_f32_e32 v245, v245
	v_mul_f32_e32 v250, 0.5, v250
	v_mul_f32_e32 v251, 0.5, v251
	v_mul_f32_e32 v252, 0.5, v252
	v_mul_f32_e32 v253, 0.5, v253
	v_add_f32_e32 v60, 1.0, v60
	v_add_f32_e32 v172, 1.0, v172
	v_add_f32_e32 v173, 1.0, v173
	v_add_f32_e32 v245, 1.0, v245
	v_rcp_f32_e32 v60, v60
	v_rcp_f32_e32 v172, v172
	v_rcp_f32_e32 v173, v173
	v_rcp_f32_e32 v245, v245
	s_nop 0
	v_fma_f32 v60, v60, -2.0, 1.0
	v_fma_f32 v172, v172, -2.0, 1.0
	v_fma_f32 v173, v173, -2.0, 1.0
	v_fma_f32 v245, v245, -2.0, 1.0
	v_add_f32_e32 v60, 1.0, v60
	v_add_f32_e32 v172, 1.0, v172
	v_add_f32_e32 v173, 1.0, v173
	v_add_f32_e32 v245, 1.0, v245
	v_mul_f32_e32 v250, v250, v60
	v_mul_f32_e32 v251, v251, v172
	v_mul_f32_e32 v252, v252, v173
	v_mul_f32_e32 v253, v253, v245
	v_cvt_pk_bf16_f32 v250, v250, 0
	v_cvt_pk_bf16_f32 v251, v251, 0
	v_cvt_pk_bf16_f32 v252, v252, 0
	v_cvt_pk_bf16_f32 v253, v253, 0
	s_cmp_lg_u32 s35, 0
	s_cselect_b32 s4, 0, -1
	s_mov_b32 exec_hi, s4
	global_store_short v233, v250, s[86:87]
	global_store_short v241, v251, s[86:87]
	global_store_short v242, v252, s[86:87]
	global_store_short v243, v253, s[86:87]
	s_mov_b32 exec_hi, -1
	s_cmp_lg_u32 s35, 0
	s_cbranch_scc1 .Ls5b_ep_skip1
	ds_read_b128 v[164:167], v230 offset:4352
	ds_read_b128 v[168:171], v230 offset:4416
	ds_read_b128 v[156:159], v230 offset:4480
	ds_read_b128 v[132:135], v230 offset:4544
	ds_read_b32 v56, v232 offset:1024
	ds_read_b32 v57, v232 offset:1088
	ds_read_b32 v58, v232 offset:1152
	ds_read_b32 v59, v232 offset:1216
	s_waitcnt lgkmcnt(7)
	v_mfma_f32_16x16x32_bf16 v[250:253], v[164:167], v[208:211], 0
	s_waitcnt lgkmcnt(6)
	v_mfma_f32_16x16x32_bf16 v[250:253], v[168:171], v[212:215], v[250:253]
	s_waitcnt lgkmcnt(5)
	v_mfma_f32_16x16x32_bf16 v[250:253], v[156:159], v[216:219], v[250:253]
	s_waitcnt lgkmcnt(4)
	v_mfma_f32_16x16x32_bf16 v[250:253], v[132:135], v[220:223], v[250:253]
	s_waitcnt lgkmcnt(0)
	s_nop 7
	s_nop 1
	v_fma_f32 v250, v224, v56, v250
	v_fma_f32 v251, v224, v57, v251
	v_fma_f32 v252, v224, v58, v252
	v_fma_f32 v253, v224, v59, v253
	v_mul_f32_e32 v60, 0x3d372713, v250
	v_mul_f32_e32 v172, 0x3d372713, v251
	v_mul_f32_e32 v173, 0x3d372713, v252
	v_mul_f32_e32 v245, 0x3d372713, v253
	v_mul_f32_e32 v60, v250, v60
	v_mul_f32_e32 v172, v251, v172
	v_mul_f32_e32 v173, v252, v173
	v_mul_f32_e32 v245, v253, v245
	v_fma_f32 v60, v250, v60, v250
	v_fma_f32 v172, v251, v172, v251
	v_fma_f32 v173, v252, v173, v252
	v_fma_f32 v245, v253, v245, v253
	v_mul_f32_e32 v60, 0x3f4c422a, v60
	v_mul_f32_e32 v172, 0x3f4c422a, v172
	v_mul_f32_e32 v173, 0x3f4c422a, v173
	v_mul_f32_e32 v245, 0x3f4c422a, v245
	v_add_f32_e32 v60, v60, v60
	v_add_f32_e32 v172, v172, v172
	v_add_f32_e32 v173, v173, v173
	v_add_f32_e32 v245, v245, v245
	v_mul_f32_e32 v60, 0x3fb8aa3b, v60
	v_mul_f32_e32 v172, 0x3fb8aa3b, v172
	v_mul_f32_e32 v173, 0x3fb8aa3b, v173
	v_mul_f32_e32 v245, 0x3fb8aa3b, v245
	v_exp_f32_e32 v60, v60
	v_exp_f32_e32 v172, v172
	v_exp_f32_e32 v173, v173
	v_exp_f32_e32 v245, v245
	v_mul_f32_e32 v250, 0.5, v250
	v_mul_f32_e32 v251, 0.5, v251
	v_mul_f32_e32 v252, 0.5, v252
	v_mul_f32_e32 v253, 0.5, v253
	v_add_f32_e32 v60, 1.0, v60
	v_add_f32_e32 v172, 1.0, v172
	v_add_f32_e32 v173, 1.0, v173
	v_add_f32_e32 v245, 1.0, v245
	v_rcp_f32_e32 v60, v60
	v_rcp_f32_e32 v172, v172
	v_rcp_f32_e32 v173, v173
	v_rcp_f32_e32 v245, v245
	s_nop 0
	v_fma_f32 v60, v60, -2.0, 1.0
	v_fma_f32 v172, v172, -2.0, 1.0
	v_fma_f32 v173, v173, -2.0, 1.0
	v_fma_f32 v245, v245, -2.0, 1.0
	v_add_f32_e32 v60, 1.0, v60
	v_add_f32_e32 v172, 1.0, v172
	v_add_f32_e32 v173, 1.0, v173
	v_add_f32_e32 v245, 1.0, v245
	v_mul_f32_e32 v250, v250, v60
	v_mul_f32_e32 v251, v251, v172
	v_mul_f32_e32 v252, v252, v173
	v_mul_f32_e32 v253, v253, v245
	v_cvt_pk_bf16_f32 v250, v250, 0
	v_cvt_pk_bf16_f32 v251, v251, 0
	v_cvt_pk_bf16_f32 v252, v252, 0
	v_cvt_pk_bf16_f32 v253, v253, 0
	global_store_short v233, v250, s[88:89]
	global_store_short v241, v251, s[88:89]
	global_store_short v242, v252, s[88:89]
	global_store_short v243, v253, s[88:89]
.Ls5b_ep_skip1:
.Ls5b_item_end:
	s_cmp_lg_u32 s35, 0
	s_cbranch_scc1 .Ls5b_fin_s
	s_cmpk_lg_i32 s52, 0x7f
	s_cbranch_scc1 .Ls5b_next
	v_cndmask_b32_e64 v56, v128, v130, s[8:9]
	v_cndmask_b32_e64 v57, v129, v131, s[8:9]
	s_lshl_b32 s4, s46, 15
	s_add_u32 s4, s4, 0x4100000
	s_add_u32 s6, s72, s4
	s_addc_u32 s7, s73, 0
	global_store_dwordx2 v207, v[56:57], s[6:7]
	s_branch .Ls5b_next
.Ls5b_fin_s:
	v_cndmask_b32_e64 v56, v246, v248, s[8:9]
	v_cndmask_b32_e64 v57, v247, v249, s[8:9]
	s_lshl_b32 s4, s46, 15
	s_add_u32 s4, s4, 0x7110000
	s_add_u32 s6, s72, s4
	s_addc_u32 s7, s73, 0
	global_store_dwordx2 v207, v[56:57], s[6:7]
.Ls5b_next:
	s_add_i32 s82, s82, 0x100
	s_cmpk_lt_i32 s82, 0x900
	s_cbranch_scc1 .Ls5b_item
